# GEMM K-loops: the redundant mid-segment s_setprio 0 / s_setprio 1 pair between the two 16-MFMA blocks removed (16 sites); on union stack
# baseline (speedup 1.0000x reference)
; #define PG8_STAGE(bufoff, gbase, voff) do { _Pragma("unroll") for (int _i = 0; _i < 2; ++_i) \
;         __builtin_amdgcn_global_load_lds((const unsigned*)((const char*)(gbase) + (voff)[_i]), (PG8_LAS unsigned*)(lds + (bufoff) + ldsw + _i * 8192), 16, 0, 0); } while (0)
; #define PG8_LDA(dst, b, h) do { _Pragma("unroll") for (int m = 0; m < 4; ++m) _Pragma("unroll") for (int k = 0; k < 2; ++k) dst[m][k] = *(const PG8_LAS bf16x8*)(lds + PG8_SA(b, h) + aoff + m * 2048 + k * 1024); } while (0)
; #define PG8_LDB(dst, b, h) do { _Pragma("unroll") for (int n = 0; n < 2; ++n) _Pragma("unroll") for (int k = 0; k < 2; ++k) dst[n][k] = *(const PG8_LAS bf16x8*)(lds + PG8_SB(b, h) + boff + n * 2048 + k * 1024); } while (0)
; #define PG8_MMA(ai, bj, At, Bt) do { __builtin_amdgcn_s_setprio(1); _Pragma("unroll") for (int m = 0; m < 4; ++m) _Pragma("unroll") for (int n = 0; n < 2; ++n) _Pragma("unroll") for (int k = 0; k < 2; ++k) \
;         acc[ai][bj][m][n] = __builtin_amdgcn_mfma_f32_16x16x32_bf16(Bt[n][k], At[m][k], acc[ai][bj][m][n], 0, 0, 0); __builtin_amdgcn_s_setprio(0); } while (0)
; #define PG8_WAIT_V(n) asm volatile("s_waitcnt vmcnt(" #n ")" ::: "memory")
; #define PG8_WAIT_L(n) asm volatile("s_waitcnt lgkmcnt(" #n ")" ::: "memory")
; #define PG8_BAR __builtin_amdgcn_s_barrier()
; #define PG8_SCHED __builtin_amdgcn_sched_barrier(0)
; template <class Epi, class Sched, bool ALIGN_EPI = false, bool SP2 = false>
; __device__ __forceinline__ void gemm_phase(PG8_LAS unsigned char* lds, const Gemm g, const Sched& S, const Epi& E) {
;     ...
;             PG8_LDB(B0, 0, 0); PG8_LDB(B1, 0, 1); PG8_SCHED; PG8_LDA(At, 0, 0); PG8_STAGE(PG8_SA(1, 1), a1 + hstep, voffA);
;             PG8_WAIT_V(8); PG8_WAIT_L(0); PG8_BAR; PG8_MMA(0, 0, At, B0); PG8_MMA(0, 1, At, B1); PG8_BAR; PG8_SCHED;
;             PG8_LDA(At, 0, 1); PG8_STAGE(PG8_SB(0, 0), b2, voffB); PG8_STAGE(PG8_SB(0, 1), b2 + hstepB, voffB); PG8_STAGE(PG8_SA(0, 0), a2, voffA);
;             PG8_WAIT_V(8); PG8_WAIT_L(0); PG8_BAR; PG8_MMA(1, 0, At, B0); PG8_MMA(1, 1, At, B1); PG8_BAR; PG8_SCHED;
.LBB0_402:
	ds_read_b128 v[82:85], v178
	ds_read_b128 v[86:89], v178 offset:1024
	ds_read_b128 v[90:93], v178 offset:2048
	ds_read_b128 v[94:97], v178 offset:3072
	ds_read_b128 v[186:189], v179
	ds_read_b128 v[190:193], v179 offset:1024
	ds_read_b128 v[194:197], v179 offset:2048
	ds_read_b128 v[198:201], v179 offset:3072
	s_add_u32 s10, s6, 0xfff00080
	s_addc_u32 s11, s7, -1
	s_cmp_eq_u32 s51, 60
	s_cselect_b32 s35, s23, s11
	s_cselect_b32 s34, s47, s10
	s_cselect_b32 s11, s21, s50
	s_cselect_b32 s10, s48, s49
	v_lshl_add_u64 v[234:235], s[6:7], 0, v[158:159]
	s_add_i32 m0, s29, 0xc000
	ds_read_b128 v[202:205], v180
	ds_read_b128 v[206:209], v180 offset:1024
	ds_read_b128 v[210:213], v180 offset:2048
	ds_read_b128 v[214:217], v180 offset:3072
	ds_read_b128 v[218:221], v180 offset:4096
	ds_read_b128 v[222:225], v180 offset:5120
	ds_read_b128 v[226:229], v180 offset:6144
	ds_read_b128 v[230:233], v180 offset:7168
	global_load_lds_dwordx4 v[234:235], off
	v_lshl_add_u64 v[234:235], s[6:7], 0, v[160:161]
	s_add_i32 m0, s29, 0xe000
	s_nop 0
	global_load_lds_dwordx4 v[234:235], off
	s_waitcnt vmcnt(8)
	s_waitcnt lgkmcnt(0)
	s_barrier
	s_setprio 1
	s_waitcnt lgkmcnt(0)
	v_mfma_f32_16x16x32_bf16 v[142:145], v[82:85], v[202:205], v[142:145]
	v_mfma_f32_16x16x32_bf16 v[142:145], v[86:89], v[206:209], v[142:145]
	v_mfma_f32_16x16x32_bf16 v[138:141], v[90:93], v[202:205], v[138:141]
	v_mfma_f32_16x16x32_bf16 v[138:141], v[94:97], v[206:209], v[138:141]
	v_mfma_f32_16x16x32_bf16 v[126:129], v[82:85], v[210:213], v[126:129]
	v_mfma_f32_16x16x32_bf16 v[126:129], v[86:89], v[214:217], v[126:129]
	v_mfma_f32_16x16x32_bf16 v[122:125], v[90:93], v[210:213], v[122:125]
	v_mfma_f32_16x16x32_bf16 v[122:125], v[94:97], v[214:217], v[122:125]
	v_mfma_f32_16x16x32_bf16 v[110:113], v[82:85], v[218:221], v[110:113]
	v_mfma_f32_16x16x32_bf16 v[110:113], v[86:89], v[222:225], v[110:113]
	v_mfma_f32_16x16x32_bf16 v[106:109], v[90:93], v[218:221], v[106:109]
	v_mfma_f32_16x16x32_bf16 v[106:109], v[94:97], v[222:225], v[106:109]
	v_mfma_f32_16x16x32_bf16 v[78:81], v[82:85], v[226:229], v[78:81]
	v_mfma_f32_16x16x32_bf16 v[78:81], v[86:89], v[230:233], v[78:81]
	v_mfma_f32_16x16x32_bf16 v[74:77], v[90:93], v[226:229], v[74:77]
	v_mfma_f32_16x16x32_bf16 v[74:77], v[94:97], v[230:233], v[74:77]
	v_mfma_f32_16x16x32_bf16 v[134:137], v[186:189], v[202:205], v[134:137]
	v_mfma_f32_16x16x32_bf16 v[134:137], v[190:193], v[206:209], v[134:137]
	v_mfma_f32_16x16x32_bf16 v[130:133], v[194:197], v[202:205], v[130:133]
	v_mfma_f32_16x16x32_bf16 v[130:133], v[198:201], v[206:209], v[130:133]
	v_mfma_f32_16x16x32_bf16 v[118:121], v[186:189], v[210:213], v[118:121]
	v_mfma_f32_16x16x32_bf16 v[118:121], v[190:193], v[214:217], v[118:121]
	v_mfma_f32_16x16x32_bf16 v[114:117], v[194:197], v[210:213], v[114:117]
	v_mfma_f32_16x16x32_bf16 v[114:117], v[198:201], v[214:217], v[114:117]
	v_mfma_f32_16x16x32_bf16 v[102:105], v[186:189], v[218:221], v[102:105]
	v_mfma_f32_16x16x32_bf16 v[102:105], v[190:193], v[222:225], v[102:105]
	v_mfma_f32_16x16x32_bf16 v[98:101], v[194:197], v[218:221], v[98:101]
	v_mfma_f32_16x16x32_bf16 v[98:101], v[198:201], v[222:225], v[98:101]
	v_mfma_f32_16x16x32_bf16 v[70:73], v[186:189], v[226:229], v[70:73]
	v_mfma_f32_16x16x32_bf16 v[70:73], v[190:193], v[230:233], v[70:73]
	v_mfma_f32_16x16x32_bf16 v[66:69], v[194:197], v[226:229], v[66:69]
	v_mfma_f32_16x16x32_bf16 v[66:69], v[198:201], v[230:233], v[66:69]
	s_setprio 0
	s_barrier
	s_add_i32 s52, s42, s37
	v_lshl_add_u64 v[234:235], s[10:11], 0, v[148:149]
	s_mov_b32 m0, s52
	ds_read_b128 v[202:205], v180 offset:16384
	ds_read_b128 v[206:209], v180 offset:17408
	ds_read_b128 v[210:213], v180 offset:18432
	ds_read_b128 v[214:217], v180 offset:19456
	ds_read_b128 v[218:221], v180 offset:20480
	ds_read_b128 v[222:225], v180 offset:21504
	ds_read_b128 v[226:229], v180 offset:22528
	ds_read_b128 v[230:233], v180 offset:23552
	global_load_lds_dwordx4 v[234:235], off
	s_add_i32 m0, s52, 0x2000
	s_add_u32 s52, s10, 0x40000
	v_lshl_add_u64 v[236:237], s[10:11], 0, v[152:153]
	s_addc_u32 s53, s11, 0
	s_add_i32 s54, s43, s37
	global_load_lds_dwordx4 v[236:237], off
	v_lshl_add_u64 v[238:239], s[52:53], 0, v[148:149]
	s_mov_b32 m0, s54
	v_lshl_add_u64 v[240:241], s[34:35], 0, v[150:151]
	global_load_lds_dwordx4 v[238:239], off
	v_lshl_add_u64 v[238:239], s[52:53], 0, v[152:153]
	s_add_i32 m0, s54, 0x2000
	s_nop 0
	global_load_lds_dwordx4 v[238:239], off
	v_lshl_add_u64 v[238:239], s[34:35], 0, v[146:147]
	s_mov_b32 m0, s29
	s_nop 0
	global_load_lds_dwordx4 v[238:239], off
	s_mov_b32 m0, s31
	s_nop 0
	global_load_lds_dwordx4 v[240:241], off
	s_waitcnt vmcnt(8)
	s_waitcnt lgkmcnt(0)
	s_barrier
; #define PG8_STAGE(bufoff, gbase, voff) do { _Pragma("unroll") for (int _i = 0; _i < 2; ++_i) \
;         __builtin_amdgcn_global_load_lds((const unsigned*)((const char*)(gbase) + (voff)[_i]), (PG8_LAS unsigned*)(lds + (bufoff) + ldsw + _i * 8192), 16, 0, 0); } while (0)
; #define PG8_LDA(dst, b, h) do { _Pragma("unroll") for (int m = 0; m < 4; ++m) _Pragma("unroll") for (int k = 0; k < 2; ++k) dst[m][k] = *(const PG8_LAS bf16x8*)(lds + PG8_SA(b, h) + aoff + m * 2048 + k * 1024); } while (0)
; #define PG8_LDB(dst, b, h) do { _Pragma("unroll") for (int n = 0; n < 2; ++n) _Pragma("unroll") for (int k = 0; k < 2; ++k) dst[n][k] = *(const PG8_LAS bf16x8*)(lds + PG8_SB(b, h) + boff + n * 2048 + k * 1024); } while (0)
; #define PG8_MMA(ai, bj, At, Bt) do { __builtin_amdgcn_s_setprio(1); _Pragma("unroll") for (int m = 0; m < 4; ++m) _Pragma("unroll") for (int n = 0; n < 2; ++n) _Pragma("unroll") for (int k = 0; k < 2; ++k) \
;         acc[ai][bj][m][n] = __builtin_amdgcn_mfma_f32_16x16x32_bf16(Bt[n][k], At[m][k], acc[ai][bj][m][n], 0, 0, 0); __builtin_amdgcn_s_setprio(0); } while (0)
; #define PG8_WAIT_V(n) asm volatile("s_waitcnt vmcnt(" #n ")" ::: "memory")
; #define PG8_WAIT_L(n) asm volatile("s_waitcnt lgkmcnt(" #n ")" ::: "memory")
; #define PG8_BAR __builtin_amdgcn_s_barrier()
; #define PG8_SCHED __builtin_amdgcn_sched_barrier(0)
; template <class Epi, class Sched, bool ALIGN_EPI = false, bool SP2 = false>
; __device__ __forceinline__ void gemm_phase(PG8_LAS unsigned char* lds, const Gemm g, const Sched& S, const Epi& E) {
;     ...
;             PG8_WAIT_V(8); PG8_WAIT_L(0); PG8_BAR; PG8_MMA(1, 0, At, B0); PG8_MMA(1, 1, At, B1); PG8_BAR; PG8_SCHED;
;             PG8_LDB(B0, 1, 0); PG8_LDB(B1, 1, 1); PG8_SCHED; PG8_LDA(At, 1, 0); PG8_STAGE(PG8_SA(0, 1), a2 + hstep, voffA);
;             PG8_WAIT_V(8); PG8_WAIT_L(0); PG8_BAR; PG8_MMA(0, 0, At, B0); PG8_MMA(0, 1, At, B1); PG8_BAR; PG8_SCHED;
	s_setprio 1
	s_waitcnt lgkmcnt(0)
	v_mfma_f32_16x16x32_bf16 v[62:65], v[82:85], v[202:205], v[62:65]
	v_mfma_f32_16x16x32_bf16 v[62:65], v[86:89], v[206:209], v[62:65]
	v_mfma_f32_16x16x32_bf16 v[58:61], v[90:93], v[202:205], v[58:61]
	v_mfma_f32_16x16x32_bf16 v[58:61], v[94:97], v[206:209], v[58:61]
	v_mfma_f32_16x16x32_bf16 v[46:49], v[82:85], v[210:213], v[46:49]
	v_mfma_f32_16x16x32_bf16 v[46:49], v[86:89], v[214:217], v[46:49]
	v_mfma_f32_16x16x32_bf16 v[42:45], v[90:93], v[210:213], v[42:45]
	v_mfma_f32_16x16x32_bf16 v[42:45], v[94:97], v[214:217], v[42:45]
	v_mfma_f32_16x16x32_bf16 v[30:33], v[82:85], v[218:221], v[30:33]
	v_mfma_f32_16x16x32_bf16 v[30:33], v[86:89], v[222:225], v[30:33]
	v_mfma_f32_16x16x32_bf16 v[26:29], v[90:93], v[218:221], v[26:29]
	v_mfma_f32_16x16x32_bf16 v[26:29], v[94:97], v[222:225], v[26:29]
	v_mfma_f32_16x16x32_bf16 v[14:17], v[82:85], v[226:229], v[14:17]
	v_mfma_f32_16x16x32_bf16 v[14:17], v[86:89], v[230:233], v[14:17]
	v_mfma_f32_16x16x32_bf16 v[10:13], v[90:93], v[226:229], v[10:13]
	v_mfma_f32_16x16x32_bf16 v[10:13], v[94:97], v[230:233], v[10:13]
	v_mfma_f32_16x16x32_bf16 v[54:57], v[186:189], v[202:205], v[54:57]
	v_mfma_f32_16x16x32_bf16 v[54:57], v[190:193], v[206:209], v[54:57]
	v_mfma_f32_16x16x32_bf16 v[50:53], v[194:197], v[202:205], v[50:53]
	v_mfma_f32_16x16x32_bf16 v[50:53], v[198:201], v[206:209], v[50:53]
	v_mfma_f32_16x16x32_bf16 v[38:41], v[186:189], v[210:213], v[38:41]
	v_mfma_f32_16x16x32_bf16 v[38:41], v[190:193], v[214:217], v[38:41]
	v_mfma_f32_16x16x32_bf16 v[34:37], v[194:197], v[210:213], v[34:37]
	v_mfma_f32_16x16x32_bf16 v[34:37], v[198:201], v[214:217], v[34:37]
	v_mfma_f32_16x16x32_bf16 v[22:25], v[186:189], v[218:221], v[22:25]
	v_mfma_f32_16x16x32_bf16 v[22:25], v[190:193], v[222:225], v[22:25]
	v_mfma_f32_16x16x32_bf16 v[18:21], v[194:197], v[218:221], v[18:21]
	v_mfma_f32_16x16x32_bf16 v[18:21], v[198:201], v[222:225], v[18:21]
	v_mfma_f32_16x16x32_bf16 v[6:9], v[186:189], v[226:229], v[6:9]
	v_mfma_f32_16x16x32_bf16 v[6:9], v[190:193], v[230:233], v[6:9]
	v_mfma_f32_16x16x32_bf16 v[2:5], v[194:197], v[226:229], v[2:5]
	v_mfma_f32_16x16x32_bf16 v[2:5], v[198:201], v[230:233], v[2:5]
	s_setprio 0
	s_barrier
	s_add_i32 s52, 0, 0x18000
	s_add_i32 s53, 0, 0x1c000
	v_add_u32_e32 v94, s52, v1
	v_add_u32_e32 v167, s53, v1
	ds_read_b128 v[82:85], v94
	ds_read_b128 v[86:89], v94 offset:1024
	ds_read_b128 v[90:93], v94 offset:2048
	ds_read_b128 v[94:97], v94 offset:3072
	ds_read_b128 v[186:189], v167
	ds_read_b128 v[190:193], v167 offset:1024
	ds_read_b128 v[194:197], v167 offset:2048
	ds_read_b128 v[198:201], v167 offset:3072
	s_add_u32 s34, s34, 0x100000
	s_addc_u32 s35, s35, 0
	s_mov_b32 m0, s38
	v_lshl_add_u64 v[242:243], s[34:35], 0, v[146:147]
	ds_read_b128 v[202:205], v180 offset:32768
	ds_read_b128 v[206:209], v180 offset:33792
	ds_read_b128 v[210:213], v180 offset:34816
	ds_read_b128 v[214:217], v180 offset:35840
	ds_read_b128 v[218:221], v180 offset:36864
	ds_read_b128 v[222:225], v180 offset:37888
	ds_read_b128 v[226:229], v180 offset:38912
	ds_read_b128 v[230:233], v180 offset:39936
	global_load_lds_dwordx4 v[242:243], off
	v_lshl_add_u64 v[242:243], s[34:35], 0, v[150:151]
	s_mov_b32 m0, s39
	s_nop 0
	global_load_lds_dwordx4 v[242:243], off
	s_waitcnt vmcnt(8)
	s_waitcnt lgkmcnt(0)
	s_barrier
	s_setprio 1
	s_waitcnt lgkmcnt(0)
	v_mfma_f32_16x16x32_bf16 v[142:145], v[82:85], v[202:205], v[142:145]
	v_mfma_f32_16x16x32_bf16 v[142:145], v[86:89], v[206:209], v[142:145]
	v_mfma_f32_16x16x32_bf16 v[138:141], v[90:93], v[202:205], v[138:141]
	v_mfma_f32_16x16x32_bf16 v[138:141], v[94:97], v[206:209], v[138:141]
	v_mfma_f32_16x16x32_bf16 v[126:129], v[82:85], v[210:213], v[126:129]
	v_mfma_f32_16x16x32_bf16 v[126:129], v[86:89], v[214:217], v[126:129]
	v_mfma_f32_16x16x32_bf16 v[122:125], v[90:93], v[210:213], v[122:125]
	v_mfma_f32_16x16x32_bf16 v[122:125], v[94:97], v[214:217], v[122:125]
	v_mfma_f32_16x16x32_bf16 v[110:113], v[82:85], v[218:221], v[110:113]
	v_mfma_f32_16x16x32_bf16 v[110:113], v[86:89], v[222:225], v[110:113]
	v_mfma_f32_16x16x32_bf16 v[106:109], v[90:93], v[218:221], v[106:109]
	v_mfma_f32_16x16x32_bf16 v[106:109], v[94:97], v[222:225], v[106:109]
	v_mfma_f32_16x16x32_bf16 v[78:81], v[82:85], v[226:229], v[78:81]
	v_mfma_f32_16x16x32_bf16 v[78:81], v[86:89], v[230:233], v[78:81]
	v_mfma_f32_16x16x32_bf16 v[74:77], v[90:93], v[226:229], v[74:77]
	v_mfma_f32_16x16x32_bf16 v[74:77], v[94:97], v[230:233], v[74:77]
	v_mfma_f32_16x16x32_bf16 v[134:137], v[186:189], v[202:205], v[134:137]
	v_mfma_f32_16x16x32_bf16 v[134:137], v[190:193], v[206:209], v[134:137]
	v_mfma_f32_16x16x32_bf16 v[130:133], v[194:197], v[202:205], v[130:133]
	v_mfma_f32_16x16x32_bf16 v[130:133], v[198:201], v[206:209], v[130:133]
	v_mfma_f32_16x16x32_bf16 v[118:121], v[186:189], v[210:213], v[118:121]
	v_mfma_f32_16x16x32_bf16 v[118:121], v[190:193], v[214:217], v[118:121]
	v_mfma_f32_16x16x32_bf16 v[114:117], v[194:197], v[210:213], v[114:117]
	v_mfma_f32_16x16x32_bf16 v[114:117], v[198:201], v[214:217], v[114:117]
	v_mfma_f32_16x16x32_bf16 v[102:105], v[186:189], v[218:221], v[102:105]
	v_mfma_f32_16x16x32_bf16 v[102:105], v[190:193], v[222:225], v[102:105]
	v_mfma_f32_16x16x32_bf16 v[98:101], v[194:197], v[218:221], v[98:101]
	v_mfma_f32_16x16x32_bf16 v[98:101], v[198:201], v[222:225], v[98:101]
	v_mfma_f32_16x16x32_bf16 v[70:73], v[186:189], v[226:229], v[70:73]
	v_mfma_f32_16x16x32_bf16 v[70:73], v[190:193], v[230:233], v[70:73]
	v_mfma_f32_16x16x32_bf16 v[66:69], v[194:197], v[226:229], v[66:69]
	v_mfma_f32_16x16x32_bf16 v[66:69], v[198:201], v[230:233], v[66:69]
	s_setprio 0
	s_barrier
; #define PG8_STAGE(bufoff, gbase, voff) do { _Pragma("unroll") for (int _i = 0; _i < 2; ++_i) \
;         __builtin_amdgcn_global_load_lds((const unsigned*)((const char*)(gbase) + (voff)[_i]), (PG8_LAS unsigned*)(lds + (bufoff) + ldsw + _i * 8192), 16, 0, 0); } while (0)
; #define PG8_LDA(dst, b, h) do { _Pragma("unroll") for (int m = 0; m < 4; ++m) _Pragma("unroll") for (int k = 0; k < 2; ++k) dst[m][k] = *(const PG8_LAS bf16x8*)(lds + PG8_SA(b, h) + aoff + m * 2048 + k * 1024); } while (0)
; #define PG8_MMA(ai, bj, At, Bt) do { __builtin_amdgcn_s_setprio(1); _Pragma("unroll") for (int m = 0; m < 4; ++m) _Pragma("unroll") for (int n = 0; n < 2; ++n) _Pragma("unroll") for (int k = 0; k < 2; ++k) \
;         acc[ai][bj][m][n] = __builtin_amdgcn_mfma_f32_16x16x32_bf16(Bt[n][k], At[m][k], acc[ai][bj][m][n], 0, 0, 0); __builtin_amdgcn_s_setprio(0); } while (0)
; #define PG8_WAIT_V(n) asm volatile("s_waitcnt vmcnt(" #n ")" ::: "memory")
; #define PG8_WAIT_L(n) asm volatile("s_waitcnt lgkmcnt(" #n ")" ::: "memory")
; #define PG8_BAR __builtin_amdgcn_s_barrier()
; #define PG8_SCHED __builtin_amdgcn_sched_barrier(0)
; template <class Epi, class Sched, bool ALIGN_EPI = false, bool SP2 = false>
; __device__ __forceinline__ void gemm_phase(PG8_LAS unsigned char* lds, const Gemm g, const Sched& S, const Epi& E) {
;     ...
;         for (int t = 0; t < nt; t += 2) {
;             const bool last = (t == nt - 2);
;             const char* a1 = cA + (size_t)(t + 1) * kstep;
;             const char* a2 = last ? nA : cA + (size_t)(t + 2) * kstep; const char* b2 = last ? nB : cB + (size_t)(t + 2) * kstep;
;     ...
;             PG8_LDA(At, 1, 1); PG8_STAGE(PG8_SB(1, 0), b3, voffB); PG8_STAGE(PG8_SB(1, 1), b3 + hstepB, voffB); PG8_STAGE(PG8_SA(1, 0), a3, voffA);
;             PG8_WAIT_V(8); PG8_WAIT_L(0); PG8_BAR; PG8_MMA(1, 0, At, B0); PG8_MMA(1, 1, At, B1); PG8_BAR; PG8_SCHED;
	s_add_i32 s34, s52, s37
	v_lshl_add_u64 v[234:235], v[234:235], 0, s[16:17]
	s_mov_b32 m0, s34
	ds_read_b128 v[202:205], v180 offset:49152
	ds_read_b128 v[206:209], v180 offset:50176
	ds_read_b128 v[210:213], v180 offset:51200
	ds_read_b128 v[214:217], v180 offset:52224
	ds_read_b128 v[218:221], v180 offset:53248
	ds_read_b128 v[222:225], v180 offset:54272
	ds_read_b128 v[226:229], v180 offset:55296
	ds_read_b128 v[230:233], v180 offset:56320
	global_load_lds_dwordx4 v[234:235], off
	s_add_i32 m0, s34, 0x2000
	s_add_u32 s10, s10, 0x40080
	v_lshl_add_u64 v[234:235], v[236:237], 0, s[16:17]
	s_addc_u32 s11, s11, 0
	s_add_i32 s34, s53, s37
	global_load_lds_dwordx4 v[234:235], off
	v_lshl_add_u64 v[234:235], s[10:11], 0, v[148:149]
	s_mov_b32 m0, s34
	s_nop 0
	global_load_lds_dwordx4 v[234:235], off
	v_lshl_add_u64 v[234:235], s[10:11], 0, v[152:153]
	s_add_i32 m0, s34, 0x2000
	s_nop 0
	global_load_lds_dwordx4 v[234:235], off
	v_lshl_add_u64 v[234:235], v[238:239], 0, s[16:17]
	s_mov_b32 m0, s40
	s_nop 0
	global_load_lds_dwordx4 v[234:235], off
	v_lshl_add_u64 v[234:235], v[240:241], 0, s[16:17]
	s_mov_b32 m0, s41
	s_nop 0
	global_load_lds_dwordx4 v[234:235], off
	s_waitcnt vmcnt(8)
	s_waitcnt lgkmcnt(0)
	s_barrier
	s_setprio 1
	s_waitcnt lgkmcnt(0)
	v_mfma_f32_16x16x32_bf16 v[62:65], v[82:85], v[202:205], v[62:65]
	v_mfma_f32_16x16x32_bf16 v[62:65], v[86:89], v[206:209], v[62:65]
	v_mfma_f32_16x16x32_bf16 v[58:61], v[90:93], v[202:205], v[58:61]
	v_mfma_f32_16x16x32_bf16 v[58:61], v[94:97], v[206:209], v[58:61]
	v_mfma_f32_16x16x32_bf16 v[46:49], v[82:85], v[210:213], v[46:49]
	v_mfma_f32_16x16x32_bf16 v[46:49], v[86:89], v[214:217], v[46:49]
	v_mfma_f32_16x16x32_bf16 v[42:45], v[90:93], v[210:213], v[42:45]
	v_mfma_f32_16x16x32_bf16 v[42:45], v[94:97], v[214:217], v[42:45]
	v_mfma_f32_16x16x32_bf16 v[30:33], v[82:85], v[218:221], v[30:33]
	v_mfma_f32_16x16x32_bf16 v[30:33], v[86:89], v[222:225], v[30:33]
	v_mfma_f32_16x16x32_bf16 v[26:29], v[90:93], v[218:221], v[26:29]
	v_mfma_f32_16x16x32_bf16 v[26:29], v[94:97], v[222:225], v[26:29]
	v_mfma_f32_16x16x32_bf16 v[14:17], v[82:85], v[226:229], v[14:17]
	v_mfma_f32_16x16x32_bf16 v[14:17], v[86:89], v[230:233], v[14:17]
	v_mfma_f32_16x16x32_bf16 v[10:13], v[90:93], v[226:229], v[10:13]
	v_mfma_f32_16x16x32_bf16 v[10:13], v[94:97], v[230:233], v[10:13]
	v_mfma_f32_16x16x32_bf16 v[54:57], v[186:189], v[202:205], v[54:57]
	v_mfma_f32_16x16x32_bf16 v[54:57], v[190:193], v[206:209], v[54:57]
	v_mfma_f32_16x16x32_bf16 v[50:53], v[194:197], v[202:205], v[50:53]
	v_mfma_f32_16x16x32_bf16 v[50:53], v[198:201], v[206:209], v[50:53]
	v_mfma_f32_16x16x32_bf16 v[38:41], v[186:189], v[210:213], v[38:41]
	v_mfma_f32_16x16x32_bf16 v[38:41], v[190:193], v[214:217], v[38:41]
	v_mfma_f32_16x16x32_bf16 v[34:37], v[194:197], v[210:213], v[34:37]
	v_mfma_f32_16x16x32_bf16 v[34:37], v[198:201], v[214:217], v[34:37]
	v_mfma_f32_16x16x32_bf16 v[22:25], v[186:189], v[218:221], v[22:25]
	v_mfma_f32_16x16x32_bf16 v[22:25], v[190:193], v[222:225], v[22:25]
	v_mfma_f32_16x16x32_bf16 v[18:21], v[194:197], v[218:221], v[18:21]
	v_mfma_f32_16x16x32_bf16 v[18:21], v[198:201], v[222:225], v[18:21]
	v_mfma_f32_16x16x32_bf16 v[6:9], v[186:189], v[226:229], v[6:9]
	v_mfma_f32_16x16x32_bf16 v[6:9], v[190:193], v[230:233], v[6:9]
	v_mfma_f32_16x16x32_bf16 v[2:5], v[194:197], v[226:229], v[2:5]
	v_mfma_f32_16x16x32_bf16 v[2:5], v[198:201], v[230:233], v[2:5]
	s_setprio 0
	s_barrier
	s_add_i32 s51, s51, 2
	s_add_u32 s6, s6, 0x100
	s_addc_u32 s7, s7, 0
	s_add_u32 s49, s49, 0x100
	s_addc_u32 s50, s50, 0
	s_cmp_gt_u32 s51, 61
	s_cbranch_scc0 .LBB0_402
	s_and_b64 vcc, exec, s[18:19]
	s_cbranch_vccz .LBB0_405
	s_barrier

; #define PG8_STAGE(bufoff, gbase, voff) do { _Pragma("unroll") for (int _i = 0; _i < 2; ++_i) \
;         __builtin_amdgcn_global_load_lds((const unsigned*)((const char*)(gbase) + (voff)[_i]), (PG8_LAS unsigned*)(lds + (bufoff) + ldsw + _i * 8192), 16, 0, 0); } while (0)
; #define PG8_LDA(dst, b, h) do { _Pragma("unroll") for (int m = 0; m < 4; ++m) _Pragma("unroll") for (int k = 0; k < 2; ++k) dst[m][k] = *(const PG8_LAS bf16x8*)(lds + PG8_SA(b, h) + aoff + m * 2048 + k * 1024); } while (0)
; #define PG8_LDB(dst, b, h) do { _Pragma("unroll") for (int n = 0; n < 2; ++n) _Pragma("unroll") for (int k = 0; k < 2; ++k) dst[n][k] = *(const PG8_LAS bf16x8*)(lds + PG8_SB(b, h) + boff + n * 2048 + k * 1024); } while (0)
; #define PG8_MMA(ai, bj, At, Bt) do { __builtin_amdgcn_s_setprio(1); _Pragma("unroll") for (int m = 0; m < 4; ++m) _Pragma("unroll") for (int n = 0; n < 2; ++n) _Pragma("unroll") for (int k = 0; k < 2; ++k) \
;         acc[ai][bj][m][n] = __builtin_amdgcn_mfma_f32_16x16x32_bf16(Bt[n][k], At[m][k], acc[ai][bj][m][n], 0, 0, 0); __builtin_amdgcn_s_setprio(0); } while (0)
; #define PG8_WAIT_V(n) asm volatile("s_waitcnt vmcnt(" #n ")" ::: "memory")
; #define PG8_BAR __builtin_amdgcn_s_barrier()
; template <class Epi, class Sched, bool ALIGN_EPI = false, bool SP2 = false>
; __device__ __forceinline__ void gemm_phase(PG8_LAS unsigned char* lds, const Gemm g, const Sched& S, const Epi& E) {
;     ...
;         for (int t = 0; t < nt; t += 2) {
;             const bool last = (t == nt - 2);
;             const char* a1 = cA + (size_t)(t + 1) * kstep;
;             const char* a2 = last ? nA : cA + (size_t)(t + 2) * kstep; const char* b2 = last ? nB : cB + (size_t)(t + 2) * kstep;
;             const char* a3 = a2 + kstep; const char* b3 = b2 + kstep;
;             if (last && has_next) S.a_ready(nxt);
;             if constexpr (SP2) {
;             PG8_LDB(B0, 0, 0); PG8_LDB(B1, 0, 1); PG8_SCHED; PG8_LDA(At, 0, 0); PG8_STAGE(PG8_SA(1, 1), a1 + hstep, voffA);
;             PG8_WAIT_V(8); PG8_WAIT_L(0); PG8_BAR; PG8_MMA(0, 0, At, B0); PG8_MMA(0, 1, At, B1); PG8_BAR; PG8_SCHED;
;             PG8_LDA(At, 0, 1); PG8_STAGE(PG8_SB(0, 0), b2, voffB); PG8_STAGE(PG8_SB(0, 1), b2 + hstepB, voffB); PG8_STAGE(PG8_SA(0, 0), a2, voffA);
;             PG8_WAIT_V(8); PG8_WAIT_L(0); PG8_BAR; PG8_MMA(1, 0, At, B0); PG8_MMA(1, 1, At, B1); PG8_BAR; PG8_SCHED;
.LBB0_1759:
	ds_read_b128 v[66:69], v168
	ds_read_b128 v[70:73], v168 offset:1024
	ds_read_b128 v[74:77], v168 offset:2048
	ds_read_b128 v[78:81], v168 offset:3072
	ds_read_b128 v[162:165], v169
	ds_read_b128 v[172:175], v169 offset:1024
	ds_read_b128 v[176:179], v169 offset:2048
	ds_read_b128 v[180:183], v169 offset:3072
	s_add_u32 s34, s30, 0xfff00080
	s_addc_u32 s35, s31, -1
	s_cmp_eq_u32 s63, 60
	s_cselect_b32 s37, s23, s35
	s_cselect_b32 s36, s59, s34
	s_cselect_b32 s35, s21, s62
	s_cselect_b32 s34, s60, s61
	v_lshl_add_u64 v[216:217], s[30:31], 0, v[154:155]
	s_add_i32 m0, s40, 0xc000
	ds_read_b128 v[184:187], v170
	ds_read_b128 v[188:191], v170 offset:1024
	ds_read_b128 v[192:195], v170 offset:2048
	ds_read_b128 v[196:199], v170 offset:3072
	ds_read_b128 v[200:203], v170 offset:4096
	ds_read_b128 v[204:207], v170 offset:5120
	ds_read_b128 v[208:211], v170 offset:6144
	ds_read_b128 v[212:215], v170 offset:7168
	global_load_lds_dwordx4 v[216:217], off
	v_lshl_add_u64 v[216:217], s[30:31], 0, v[156:157]
	s_add_i32 m0, s40, 0xe000
	s_nop 0
	global_load_lds_dwordx4 v[216:217], off
	s_waitcnt vmcnt(8)
	s_waitcnt lgkmcnt(0)
	s_barrier
	s_setprio 1
	s_waitcnt lgkmcnt(0)
	v_mfma_f32_16x16x32_bf16 v[142:145], v[66:69], v[184:187], v[142:145]
	v_mfma_f32_16x16x32_bf16 v[142:145], v[70:73], v[188:191], v[142:145]
	v_mfma_f32_16x16x32_bf16 v[138:141], v[74:77], v[184:187], v[138:141]
	v_mfma_f32_16x16x32_bf16 v[138:141], v[78:81], v[188:191], v[138:141]
	v_mfma_f32_16x16x32_bf16 v[126:129], v[66:69], v[192:195], v[126:129]
	v_mfma_f32_16x16x32_bf16 v[126:129], v[70:73], v[196:199], v[126:129]
	v_mfma_f32_16x16x32_bf16 v[122:125], v[74:77], v[192:195], v[122:125]
	v_mfma_f32_16x16x32_bf16 v[122:125], v[78:81], v[196:199], v[122:125]
	v_mfma_f32_16x16x32_bf16 v[110:113], v[66:69], v[200:203], v[110:113]
	v_mfma_f32_16x16x32_bf16 v[110:113], v[70:73], v[204:207], v[110:113]
	v_mfma_f32_16x16x32_bf16 v[106:109], v[74:77], v[200:203], v[106:109]
	v_mfma_f32_16x16x32_bf16 v[106:109], v[78:81], v[204:207], v[106:109]
	v_mfma_f32_16x16x32_bf16 v[94:97], v[66:69], v[208:211], v[94:97]
	v_mfma_f32_16x16x32_bf16 v[94:97], v[70:73], v[212:215], v[94:97]
	v_mfma_f32_16x16x32_bf16 v[90:93], v[74:77], v[208:211], v[90:93]
	v_mfma_f32_16x16x32_bf16 v[90:93], v[78:81], v[212:215], v[90:93]
	v_mfma_f32_16x16x32_bf16 v[134:137], v[162:165], v[184:187], v[134:137]
	v_mfma_f32_16x16x32_bf16 v[134:137], v[172:175], v[188:191], v[134:137]
	v_mfma_f32_16x16x32_bf16 v[130:133], v[176:179], v[184:187], v[130:133]
	v_mfma_f32_16x16x32_bf16 v[130:133], v[180:183], v[188:191], v[130:133]
	v_mfma_f32_16x16x32_bf16 v[118:121], v[162:165], v[192:195], v[118:121]
	v_mfma_f32_16x16x32_bf16 v[118:121], v[172:175], v[196:199], v[118:121]
	v_mfma_f32_16x16x32_bf16 v[114:117], v[176:179], v[192:195], v[114:117]
	v_mfma_f32_16x16x32_bf16 v[114:117], v[180:183], v[196:199], v[114:117]
	v_mfma_f32_16x16x32_bf16 v[102:105], v[162:165], v[200:203], v[102:105]
	v_mfma_f32_16x16x32_bf16 v[102:105], v[172:175], v[204:207], v[102:105]
	v_mfma_f32_16x16x32_bf16 v[98:101], v[176:179], v[200:203], v[98:101]
	v_mfma_f32_16x16x32_bf16 v[98:101], v[180:183], v[204:207], v[98:101]
	v_mfma_f32_16x16x32_bf16 v[86:89], v[162:165], v[208:211], v[86:89]
	v_mfma_f32_16x16x32_bf16 v[86:89], v[172:175], v[212:215], v[86:89]
	v_mfma_f32_16x16x32_bf16 v[82:85], v[176:179], v[208:211], v[82:85]
	v_mfma_f32_16x16x32_bf16 v[82:85], v[180:183], v[212:215], v[82:85]
	s_setprio 0
	s_barrier
	s_add_i32 s64, s50, s39
	v_lshl_add_u64 v[216:217], s[34:35], 0, v[148:149]
	s_mov_b32 m0, s64
	ds_read_b128 v[184:187], v170 offset:16384
	ds_read_b128 v[188:191], v170 offset:17408
	ds_read_b128 v[192:195], v170 offset:18432
	ds_read_b128 v[196:199], v170 offset:19456
	ds_read_b128 v[200:203], v170 offset:20480
	ds_read_b128 v[204:207], v170 offset:21504
	ds_read_b128 v[208:211], v170 offset:22528
	ds_read_b128 v[212:215], v170 offset:23552
	global_load_lds_dwordx4 v[216:217], off
	s_add_i32 m0, s64, 0x2000
	s_add_u32 s64, s34, 0x100000
	v_lshl_add_u64 v[218:219], s[34:35], 0, v[152:153]
	s_addc_u32 s65, s35, 0
	s_add_i32 s66, s51, s39
	global_load_lds_dwordx4 v[218:219], off
	v_lshl_add_u64 v[220:221], s[64:65], 0, v[148:149]
	s_mov_b32 m0, s66
	v_lshl_add_u64 v[222:223], s[36:37], 0, v[150:151]
	global_load_lds_dwordx4 v[220:221], off
	v_lshl_add_u64 v[220:221], s[64:65], 0, v[152:153]
	s_add_i32 m0, s66, 0x2000
	s_nop 0
	global_load_lds_dwordx4 v[220:221], off
	v_lshl_add_u64 v[220:221], s[36:37], 0, v[146:147]
	s_mov_b32 m0, s40
	s_nop 0
	global_load_lds_dwordx4 v[220:221], off
	s_mov_b32 m0, s41
	s_nop 0
	global_load_lds_dwordx4 v[222:223], off
	s_waitcnt vmcnt(8)
	s_waitcnt lgkmcnt(0)
	s_barrier
; #define PG8_STAGE(bufoff, gbase, voff) do { _Pragma("unroll") for (int _i = 0; _i < 2; ++_i) \
;         __builtin_amdgcn_global_load_lds((const unsigned*)((const char*)(gbase) + (voff)[_i]), (PG8_LAS unsigned*)(lds + (bufoff) + ldsw + _i * 8192), 16, 0, 0); } while (0)
; #define PG8_LDA(dst, b, h) do { _Pragma("unroll") for (int m = 0; m < 4; ++m) _Pragma("unroll") for (int k = 0; k < 2; ++k) dst[m][k] = *(const PG8_LAS bf16x8*)(lds + PG8_SA(b, h) + aoff + m * 2048 + k * 1024); } while (0)
; #define PG8_LDB(dst, b, h) do { _Pragma("unroll") for (int n = 0; n < 2; ++n) _Pragma("unroll") for (int k = 0; k < 2; ++k) dst[n][k] = *(const PG8_LAS bf16x8*)(lds + PG8_SB(b, h) + boff + n * 2048 + k * 1024); } while (0)
; #define PG8_MMA(ai, bj, At, Bt) do { __builtin_amdgcn_s_setprio(1); _Pragma("unroll") for (int m = 0; m < 4; ++m) _Pragma("unroll") for (int n = 0; n < 2; ++n) _Pragma("unroll") for (int k = 0; k < 2; ++k) \
;         acc[ai][bj][m][n] = __builtin_amdgcn_mfma_f32_16x16x32_bf16(Bt[n][k], At[m][k], acc[ai][bj][m][n], 0, 0, 0); __builtin_amdgcn_s_setprio(0); } while (0)
; #define PG8_WAIT_V(n) asm volatile("s_waitcnt vmcnt(" #n ")" ::: "memory")
; #define PG8_WAIT_L(n) asm volatile("s_waitcnt lgkmcnt(" #n ")" ::: "memory")
; #define PG8_BAR __builtin_amdgcn_s_barrier()
; #define PG8_SCHED __builtin_amdgcn_sched_barrier(0)
; template <class Epi, class Sched, bool ALIGN_EPI = false, bool SP2 = false>
; __device__ __forceinline__ void gemm_phase(PG8_LAS unsigned char* lds, const Gemm g, const Sched& S, const Epi& E) {
;     ...
;             PG8_WAIT_V(8); PG8_WAIT_L(0); PG8_BAR; PG8_MMA(1, 0, At, B0); PG8_MMA(1, 1, At, B1); PG8_BAR; PG8_SCHED;
;             PG8_LDB(B0, 1, 0); PG8_LDB(B1, 1, 1); PG8_SCHED; PG8_LDA(At, 1, 0); PG8_STAGE(PG8_SA(0, 1), a2 + hstep, voffA);
;             PG8_WAIT_V(8); PG8_WAIT_L(0); PG8_BAR; PG8_MMA(0, 0, At, B0); PG8_MMA(0, 1, At, B1); PG8_BAR; PG8_SCHED;
	s_setprio 1
	s_waitcnt lgkmcnt(0)
	v_mfma_f32_16x16x32_bf16 v[62:65], v[66:69], v[184:187], v[62:65]
	v_mfma_f32_16x16x32_bf16 v[62:65], v[70:73], v[188:191], v[62:65]
	v_mfma_f32_16x16x32_bf16 v[58:61], v[74:77], v[184:187], v[58:61]
	v_mfma_f32_16x16x32_bf16 v[58:61], v[78:81], v[188:191], v[58:61]
	v_mfma_f32_16x16x32_bf16 v[46:49], v[66:69], v[192:195], v[46:49]
	v_mfma_f32_16x16x32_bf16 v[46:49], v[70:73], v[196:199], v[46:49]
	v_mfma_f32_16x16x32_bf16 v[42:45], v[74:77], v[192:195], v[42:45]
	v_mfma_f32_16x16x32_bf16 v[42:45], v[78:81], v[196:199], v[42:45]
	v_mfma_f32_16x16x32_bf16 v[30:33], v[66:69], v[200:203], v[30:33]
	v_mfma_f32_16x16x32_bf16 v[30:33], v[70:73], v[204:207], v[30:33]
	v_mfma_f32_16x16x32_bf16 v[26:29], v[74:77], v[200:203], v[26:29]
	v_mfma_f32_16x16x32_bf16 v[26:29], v[78:81], v[204:207], v[26:29]
	v_mfma_f32_16x16x32_bf16 v[22:25], v[66:69], v[208:211], v[22:25]
	v_mfma_f32_16x16x32_bf16 v[22:25], v[70:73], v[212:215], v[22:25]
	v_mfma_f32_16x16x32_bf16 v[18:21], v[74:77], v[208:211], v[18:21]
	v_mfma_f32_16x16x32_bf16 v[18:21], v[78:81], v[212:215], v[18:21]
	v_mfma_f32_16x16x32_bf16 v[54:57], v[162:165], v[184:187], v[54:57]
	v_mfma_f32_16x16x32_bf16 v[54:57], v[172:175], v[188:191], v[54:57]
	v_mfma_f32_16x16x32_bf16 v[50:53], v[176:179], v[184:187], v[50:53]
	v_mfma_f32_16x16x32_bf16 v[50:53], v[180:183], v[188:191], v[50:53]
	v_mfma_f32_16x16x32_bf16 v[38:41], v[162:165], v[192:195], v[38:41]
	v_mfma_f32_16x16x32_bf16 v[38:41], v[172:175], v[196:199], v[38:41]
	v_mfma_f32_16x16x32_bf16 v[34:37], v[176:179], v[192:195], v[34:37]
	v_mfma_f32_16x16x32_bf16 v[34:37], v[180:183], v[196:199], v[34:37]
	v_mfma_f32_16x16x32_bf16 v[14:17], v[162:165], v[200:203], v[14:17]
	v_mfma_f32_16x16x32_bf16 v[14:17], v[172:175], v[204:207], v[14:17]
	v_mfma_f32_16x16x32_bf16 v[10:13], v[176:179], v[200:203], v[10:13]
	v_mfma_f32_16x16x32_bf16 v[10:13], v[180:183], v[204:207], v[10:13]
	v_mfma_f32_16x16x32_bf16 v[6:9], v[162:165], v[208:211], v[6:9]
	v_mfma_f32_16x16x32_bf16 v[6:9], v[172:175], v[212:215], v[6:9]
	v_mfma_f32_16x16x32_bf16 v[2:5], v[176:179], v[208:211], v[2:5]
	v_mfma_f32_16x16x32_bf16 v[2:5], v[180:183], v[212:215], v[2:5]
	s_setprio 0
	s_barrier
	s_add_i32 s64, 0, 0x18000
	s_add_i32 s65, 0, 0x1c000
	v_add_u32_e32 v78, s64, v166
	v_add_u32_e32 v171, s65, v166
	ds_read_b128 v[66:69], v78
	ds_read_b128 v[70:73], v78 offset:1024
	ds_read_b128 v[74:77], v78 offset:2048
	ds_read_b128 v[78:81], v78 offset:3072
	ds_read_b128 v[162:165], v171
	ds_read_b128 v[172:175], v171 offset:1024
	ds_read_b128 v[176:179], v171 offset:2048
	ds_read_b128 v[180:183], v171 offset:3072
	s_add_u32 s36, s36, 0x100000
	s_addc_u32 s37, s37, 0
	s_mov_b32 m0, s42
	v_lshl_add_u64 v[224:225], s[36:37], 0, v[146:147]
	ds_read_b128 v[184:187], v170 offset:32768
	ds_read_b128 v[188:191], v170 offset:33792
	ds_read_b128 v[192:195], v170 offset:34816
	ds_read_b128 v[196:199], v170 offset:35840
	ds_read_b128 v[200:203], v170 offset:36864
	ds_read_b128 v[204:207], v170 offset:37888
	ds_read_b128 v[208:211], v170 offset:38912
	ds_read_b128 v[212:215], v170 offset:39936
	global_load_lds_dwordx4 v[224:225], off
	v_lshl_add_u64 v[224:225], s[36:37], 0, v[150:151]
	s_mov_b32 m0, s43
	s_nop 0
	global_load_lds_dwordx4 v[224:225], off
	s_waitcnt vmcnt(8)
	s_waitcnt lgkmcnt(0)
	s_barrier
	s_setprio 1
	s_waitcnt lgkmcnt(0)
	v_mfma_f32_16x16x32_bf16 v[142:145], v[66:69], v[184:187], v[142:145]
	v_mfma_f32_16x16x32_bf16 v[142:145], v[70:73], v[188:191], v[142:145]
	v_mfma_f32_16x16x32_bf16 v[138:141], v[74:77], v[184:187], v[138:141]
	v_mfma_f32_16x16x32_bf16 v[138:141], v[78:81], v[188:191], v[138:141]
	v_mfma_f32_16x16x32_bf16 v[126:129], v[66:69], v[192:195], v[126:129]
	v_mfma_f32_16x16x32_bf16 v[126:129], v[70:73], v[196:199], v[126:129]
	v_mfma_f32_16x16x32_bf16 v[122:125], v[74:77], v[192:195], v[122:125]
	v_mfma_f32_16x16x32_bf16 v[122:125], v[78:81], v[196:199], v[122:125]
	v_mfma_f32_16x16x32_bf16 v[110:113], v[66:69], v[200:203], v[110:113]
	v_mfma_f32_16x16x32_bf16 v[110:113], v[70:73], v[204:207], v[110:113]
	v_mfma_f32_16x16x32_bf16 v[106:109], v[74:77], v[200:203], v[106:109]
	v_mfma_f32_16x16x32_bf16 v[106:109], v[78:81], v[204:207], v[106:109]
	v_mfma_f32_16x16x32_bf16 v[94:97], v[66:69], v[208:211], v[94:97]
	v_mfma_f32_16x16x32_bf16 v[94:97], v[70:73], v[212:215], v[94:97]
	v_mfma_f32_16x16x32_bf16 v[90:93], v[74:77], v[208:211], v[90:93]
	v_mfma_f32_16x16x32_bf16 v[90:93], v[78:81], v[212:215], v[90:93]
	v_mfma_f32_16x16x32_bf16 v[134:137], v[162:165], v[184:187], v[134:137]
	v_mfma_f32_16x16x32_bf16 v[134:137], v[172:175], v[188:191], v[134:137]
	v_mfma_f32_16x16x32_bf16 v[130:133], v[176:179], v[184:187], v[130:133]
	v_mfma_f32_16x16x32_bf16 v[130:133], v[180:183], v[188:191], v[130:133]
	v_mfma_f32_16x16x32_bf16 v[118:121], v[162:165], v[192:195], v[118:121]
	v_mfma_f32_16x16x32_bf16 v[118:121], v[172:175], v[196:199], v[118:121]
	v_mfma_f32_16x16x32_bf16 v[114:117], v[176:179], v[192:195], v[114:117]
	v_mfma_f32_16x16x32_bf16 v[114:117], v[180:183], v[196:199], v[114:117]
	v_mfma_f32_16x16x32_bf16 v[102:105], v[162:165], v[200:203], v[102:105]
	v_mfma_f32_16x16x32_bf16 v[102:105], v[172:175], v[204:207], v[102:105]
	v_mfma_f32_16x16x32_bf16 v[98:101], v[176:179], v[200:203], v[98:101]
	v_mfma_f32_16x16x32_bf16 v[98:101], v[180:183], v[204:207], v[98:101]
	v_mfma_f32_16x16x32_bf16 v[86:89], v[162:165], v[208:211], v[86:89]
	v_mfma_f32_16x16x32_bf16 v[86:89], v[172:175], v[212:215], v[86:89]
	v_mfma_f32_16x16x32_bf16 v[82:85], v[176:179], v[208:211], v[82:85]
	v_mfma_f32_16x16x32_bf16 v[82:85], v[180:183], v[212:215], v[82:85]
	s_setprio 0
	s_barrier
; #define PG8_STAGE(bufoff, gbase, voff) do { _Pragma("unroll") for (int _i = 0; _i < 2; ++_i) \
;         __builtin_amdgcn_global_load_lds((const unsigned*)((const char*)(gbase) + (voff)[_i]), (PG8_LAS unsigned*)(lds + (bufoff) + ldsw + _i * 8192), 16, 0, 0); } while (0)
; #define PG8_LDA(dst, b, h) do { _Pragma("unroll") for (int m = 0; m < 4; ++m) _Pragma("unroll") for (int k = 0; k < 2; ++k) dst[m][k] = *(const PG8_LAS bf16x8*)(lds + PG8_SA(b, h) + aoff + m * 2048 + k * 1024); } while (0)
; #define PG8_WAIT_V(n) asm volatile("s_waitcnt vmcnt(" #n ")" ::: "memory")
; template <class Epi, class Sched, bool ALIGN_EPI = false, bool SP2 = false>
; __device__ __forceinline__ void gemm_phase(PG8_LAS unsigned char* lds, const Gemm g, const Sched& S, const Epi& E) {
;     ...
;             PG8_LDA(At, 1, 1); PG8_STAGE(PG8_SB(1, 0), b3, voffB); PG8_STAGE(PG8_SB(1, 1), b3 + hstepB, voffB); PG8_STAGE(PG8_SA(1, 0), a3, voffA);
;             PG8_WAIT_V(8); PG8_WAIT_L(0); PG8_BAR; PG8_MMA(1, 0, At, B0); PG8_MMA(1, 1, At, B1); PG8_BAR; PG8_SCHED;
;             } else {
;             PG8_LDB(B0, 0, 0); PG8_SCHED; PG8_LDA(At, 0, 0); PG8_STAGE(PG8_SA(1, 1), a1 + hstep, voffA);
;             PG8_WAIT_L(8); PG8_BAR; PG8_WAIT_L(0); PG8_MMA(0, 0, At, B0); PG8_BAR; PG8_SCHED;
;             PG8_LDB(B1, 0, 1); PG8_STAGE(PG8_SB(0, 0), b2, voffB);
;             PG8_BAR; PG8_WAIT_L(0); PG8_MMA(0, 1, At, B1); PG8_BAR;
;             PG8_LDA(At, 0, 1); PG8_STAGE(PG8_SA(0, 0), a2, voffA);
;             PG8_BAR; PG8_WAIT_L(0); PG8_MMA(1, 0, At, B0); PG8_BAR; PG8_SCHED;
;             PG8_STAGE(PG8_SB(0, 1), b2 + hstepB, voffB);
;             PG8_WAIT_V(6); PG8_BAR; PG8_MMA(1, 1, At, B1); PG8_BAR;
;             PG8_LDB(B0, 1, 0); PG8_SCHED; PG8_LDA(At, 1, 0); PG8_STAGE(PG8_SA(0, 1), a2 + hstep, voffA);
;             PG8_WAIT_L(8); PG8_BAR; PG8_WAIT_L(0); PG8_MMA(0, 0, At, B0); PG8_BAR; PG8_SCHED;
;             PG8_LDB(B1, 1, 1); PG8_STAGE(PG8_SB(1, 0), b3, voffB);
;             PG8_BAR; PG8_WAIT_L(0); PG8_MMA(0, 1, At, B1); PG8_BAR;
;             PG8_LDA(At, 1, 1); PG8_STAGE(PG8_SA(1, 0), a3, voffA);
;             PG8_BAR; PG8_WAIT_L(0); PG8_MMA(1, 0, At, B0); PG8_BAR; PG8_SCHED;
;             PG8_STAGE(PG8_SB(1, 1), b3 + hstepB, voffB);
;             PG8_WAIT_V(6); PG8_BAR; PG8_MMA(1, 1, At, B1); PG8_BAR;
;             }
;         }
;         if constexpr (ALIGN_EPI) { if (wr == 0) PG8_BAR; }
	s_add_i32 s36, s64, s39
	v_lshl_add_u64 v[216:217], v[216:217], 0, s[6:7]
	s_mov_b32 m0, s36
	ds_read_b128 v[184:187], v170 offset:49152
	ds_read_b128 v[188:191], v170 offset:50176
	ds_read_b128 v[192:195], v170 offset:51200
	ds_read_b128 v[196:199], v170 offset:52224
	ds_read_b128 v[200:203], v170 offset:53248
	ds_read_b128 v[204:207], v170 offset:54272
	ds_read_b128 v[208:211], v170 offset:55296
	ds_read_b128 v[212:215], v170 offset:56320
	global_load_lds_dwordx4 v[216:217], off
	s_add_i32 m0, s36, 0x2000
	s_add_u32 s34, s34, 0x100080
	v_lshl_add_u64 v[216:217], v[218:219], 0, s[6:7]
	s_addc_u32 s35, s35, 0
	s_add_i32 s36, s65, s39
	global_load_lds_dwordx4 v[216:217], off
	v_lshl_add_u64 v[216:217], s[34:35], 0, v[148:149]
	s_mov_b32 m0, s36
	s_nop 0
	global_load_lds_dwordx4 v[216:217], off
	v_lshl_add_u64 v[216:217], s[34:35], 0, v[152:153]
	s_add_i32 m0, s36, 0x2000
	s_nop 0
	global_load_lds_dwordx4 v[216:217], off
	v_lshl_add_u64 v[216:217], v[220:221], 0, s[6:7]
	s_mov_b32 m0, s47
	s_nop 0
	global_load_lds_dwordx4 v[216:217], off
	v_lshl_add_u64 v[216:217], v[222:223], 0, s[6:7]
	s_mov_b32 m0, s48
	s_nop 0
	global_load_lds_dwordx4 v[216:217], off
	s_waitcnt vmcnt(8)
	s_waitcnt lgkmcnt(0)
	s_barrier
	s_setprio 1
	s_waitcnt lgkmcnt(0)
	v_mfma_f32_16x16x32_bf16 v[62:65], v[66:69], v[184:187], v[62:65]
	v_mfma_f32_16x16x32_bf16 v[62:65], v[70:73], v[188:191], v[62:65]
	v_mfma_f32_16x16x32_bf16 v[58:61], v[74:77], v[184:187], v[58:61]
	v_mfma_f32_16x16x32_bf16 v[58:61], v[78:81], v[188:191], v[58:61]
	v_mfma_f32_16x16x32_bf16 v[46:49], v[66:69], v[192:195], v[46:49]
	v_mfma_f32_16x16x32_bf16 v[46:49], v[70:73], v[196:199], v[46:49]
	v_mfma_f32_16x16x32_bf16 v[42:45], v[74:77], v[192:195], v[42:45]
	v_mfma_f32_16x16x32_bf16 v[42:45], v[78:81], v[196:199], v[42:45]
	v_mfma_f32_16x16x32_bf16 v[30:33], v[66:69], v[200:203], v[30:33]
	v_mfma_f32_16x16x32_bf16 v[30:33], v[70:73], v[204:207], v[30:33]
	v_mfma_f32_16x16x32_bf16 v[26:29], v[74:77], v[200:203], v[26:29]
	v_mfma_f32_16x16x32_bf16 v[26:29], v[78:81], v[204:207], v[26:29]
	v_mfma_f32_16x16x32_bf16 v[22:25], v[66:69], v[208:211], v[22:25]
	v_mfma_f32_16x16x32_bf16 v[22:25], v[70:73], v[212:215], v[22:25]
	v_mfma_f32_16x16x32_bf16 v[18:21], v[74:77], v[208:211], v[18:21]
	v_mfma_f32_16x16x32_bf16 v[18:21], v[78:81], v[212:215], v[18:21]
	v_mfma_f32_16x16x32_bf16 v[54:57], v[162:165], v[184:187], v[54:57]
	v_mfma_f32_16x16x32_bf16 v[54:57], v[172:175], v[188:191], v[54:57]
	v_mfma_f32_16x16x32_bf16 v[50:53], v[176:179], v[184:187], v[50:53]
	v_mfma_f32_16x16x32_bf16 v[50:53], v[180:183], v[188:191], v[50:53]
	v_mfma_f32_16x16x32_bf16 v[38:41], v[162:165], v[192:195], v[38:41]
	v_mfma_f32_16x16x32_bf16 v[38:41], v[172:175], v[196:199], v[38:41]
	v_mfma_f32_16x16x32_bf16 v[34:37], v[176:179], v[192:195], v[34:37]
	v_mfma_f32_16x16x32_bf16 v[34:37], v[180:183], v[196:199], v[34:37]
	v_mfma_f32_16x16x32_bf16 v[14:17], v[162:165], v[200:203], v[14:17]
	v_mfma_f32_16x16x32_bf16 v[14:17], v[172:175], v[204:207], v[14:17]
	v_mfma_f32_16x16x32_bf16 v[10:13], v[176:179], v[200:203], v[10:13]
	v_mfma_f32_16x16x32_bf16 v[10:13], v[180:183], v[204:207], v[10:13]
	v_mfma_f32_16x16x32_bf16 v[6:9], v[162:165], v[208:211], v[6:9]
	v_mfma_f32_16x16x32_bf16 v[6:9], v[172:175], v[212:215], v[6:9]
	v_mfma_f32_16x16x32_bf16 v[2:5], v[176:179], v[208:211], v[2:5]
	v_mfma_f32_16x16x32_bf16 v[2:5], v[180:183], v[212:215], v[2:5]
	s_setprio 0
	s_barrier
	s_add_i32 s63, s63, 2
	s_add_u32 s30, s30, 0x100
	s_addc_u32 s31, s31, 0
	s_add_u32 s61, s61, 0x100
	s_addc_u32 s62, s62, 0
	s_cmp_gt_u32 s63, 61
	s_cbranch_scc0 .LBB0_1759
	s_and_b64 vcc, exec, s[8:9]
	s_cbranch_vccz .LBB0_1762
	s_barrier

; #define PG8_STAGE(bufoff, gbase, voff) do { _Pragma("unroll") for (int _i = 0; _i < 2; ++_i) \
;         __builtin_amdgcn_global_load_lds((const unsigned*)((const char*)(gbase) + (voff)[_i]), (PG8_LAS unsigned*)(lds + (bufoff) + ldsw + _i * 8192), 16, 0, 0); } while (0)
; #define PG8_LDA(dst, b, h) do { _Pragma("unroll") for (int m = 0; m < 4; ++m) _Pragma("unroll") for (int k = 0; k < 2; ++k) dst[m][k] = *(const PG8_LAS bf16x8*)(lds + PG8_SA(b, h) + aoff + m * 2048 + k * 1024); } while (0)
; #define PG8_LDB(dst, b, h) do { _Pragma("unroll") for (int n = 0; n < 2; ++n) _Pragma("unroll") for (int k = 0; k < 2; ++k) dst[n][k] = *(const PG8_LAS bf16x8*)(lds + PG8_SB(b, h) + boff + n * 2048 + k * 1024); } while (0)
; #define PG8_MMA(ai, bj, At, Bt) do { __builtin_amdgcn_s_setprio(1); _Pragma("unroll") for (int m = 0; m < 4; ++m) _Pragma("unroll") for (int n = 0; n < 2; ++n) _Pragma("unroll") for (int k = 0; k < 2; ++k) \
;         acc[ai][bj][m][n] = __builtin_amdgcn_mfma_f32_16x16x32_bf16(Bt[n][k], At[m][k], acc[ai][bj][m][n], 0, 0, 0); __builtin_amdgcn_s_setprio(0); } while (0)
; #define PG8_WAIT_V(n) asm volatile("s_waitcnt vmcnt(" #n ")" ::: "memory")
; #define PG8_BAR __builtin_amdgcn_s_barrier()
; template <class Epi, class Sched, bool ALIGN_EPI = false, bool SP2 = false>
; __device__ __forceinline__ void gemm_phase(PG8_LAS unsigned char* lds, const Gemm g, const Sched& S, const Epi& E) {
;     ...
;         for (int t = 0; t < nt; t += 2) {
;             const bool last = (t == nt - 2);
;             const char* a1 = cA + (size_t)(t + 1) * kstep;
;             const char* a2 = last ? nA : cA + (size_t)(t + 2) * kstep; const char* b2 = last ? nB : cB + (size_t)(t + 2) * kstep;
;             const char* a3 = a2 + kstep; const char* b3 = b2 + kstep;
;             if (last && has_next) S.a_ready(nxt);
;             if constexpr (SP2) {
;             PG8_LDB(B0, 0, 0); PG8_LDB(B1, 0, 1); PG8_SCHED; PG8_LDA(At, 0, 0); PG8_STAGE(PG8_SA(1, 1), a1 + hstep, voffA);
;             PG8_WAIT_V(8); PG8_WAIT_L(0); PG8_BAR; PG8_MMA(0, 0, At, B0); PG8_MMA(0, 1, At, B1); PG8_BAR; PG8_SCHED;
;             PG8_LDA(At, 0, 1); PG8_STAGE(PG8_SB(0, 0), b2, voffB); PG8_STAGE(PG8_SB(0, 1), b2 + hstepB, voffB); PG8_STAGE(PG8_SA(0, 0), a2, voffA);
;             PG8_WAIT_V(8); PG8_WAIT_L(0); PG8_BAR; PG8_MMA(1, 0, At, B0); PG8_MMA(1, 1, At, B1); PG8_BAR; PG8_SCHED;
.LBB0_1889:
	ds_read_b128 v[146:149], v152
	ds_read_b128 v[156:159], v152 offset:1024
	ds_read_b128 v[160:163], v152 offset:2048
	ds_read_b128 v[164:167], v152 offset:3072
	ds_read_b128 v[168:171], v153
	ds_read_b128 v[172:175], v153 offset:1024
	ds_read_b128 v[176:179], v153 offset:2048
	ds_read_b128 v[180:183], v153 offset:3072
	s_add_u32 s16, s14, 0x100
	s_addc_u32 s17, s15, 0
	s_cmp_eq_u32 s44, 60
	s_cselect_b32 s21, s5, s17
	s_cselect_b32 s20, s4, s16
	s_cselect_b32 s19, s13, s43
	s_cselect_b32 s18, s12, s42
	v_lshl_add_u64 v[216:217], s[14:15], 0, v[138:139]
	s_add_i32 m0, s26, 0xc000
	ds_read_b128 v[184:187], v154
	ds_read_b128 v[188:191], v154 offset:1024
	ds_read_b128 v[192:195], v154 offset:2048
	ds_read_b128 v[196:199], v154 offset:3072
	ds_read_b128 v[200:203], v154 offset:4096
	ds_read_b128 v[204:207], v154 offset:5120
	ds_read_b128 v[208:211], v154 offset:6144
	ds_read_b128 v[212:215], v154 offset:7168
	global_load_lds_dwordx4 v[216:217], off
	v_lshl_add_u64 v[216:217], s[14:15], 0, v[140:141]
	s_add_i32 m0, s26, 0xe000
	s_nop 0
	global_load_lds_dwordx4 v[216:217], off
	s_waitcnt vmcnt(8)
	s_waitcnt lgkmcnt(0)
	s_barrier
	s_setprio 1
	s_waitcnt lgkmcnt(0)
	v_mfma_f32_16x16x32_bf16 v[126:129], v[146:149], v[184:187], v[126:129]
	v_mfma_f32_16x16x32_bf16 v[126:129], v[156:159], v[188:191], v[126:129]
	v_mfma_f32_16x16x32_bf16 v[122:125], v[160:163], v[184:187], v[122:125]
	v_mfma_f32_16x16x32_bf16 v[122:125], v[164:167], v[188:191], v[122:125]
	v_mfma_f32_16x16x32_bf16 v[110:113], v[146:149], v[192:195], v[110:113]
	v_mfma_f32_16x16x32_bf16 v[110:113], v[156:159], v[196:199], v[110:113]
	v_mfma_f32_16x16x32_bf16 v[106:109], v[160:163], v[192:195], v[106:109]
	v_mfma_f32_16x16x32_bf16 v[106:109], v[164:167], v[196:199], v[106:109]
	v_mfma_f32_16x16x32_bf16 v[94:97], v[146:149], v[200:203], v[94:97]
	v_mfma_f32_16x16x32_bf16 v[94:97], v[156:159], v[204:207], v[94:97]
	v_mfma_f32_16x16x32_bf16 v[90:93], v[160:163], v[200:203], v[90:93]
	v_mfma_f32_16x16x32_bf16 v[90:93], v[164:167], v[204:207], v[90:93]
	v_mfma_f32_16x16x32_bf16 v[78:81], v[146:149], v[208:211], v[78:81]
	v_mfma_f32_16x16x32_bf16 v[78:81], v[156:159], v[212:215], v[78:81]
	v_mfma_f32_16x16x32_bf16 v[74:77], v[160:163], v[208:211], v[74:77]
	v_mfma_f32_16x16x32_bf16 v[74:77], v[164:167], v[212:215], v[74:77]
	v_mfma_f32_16x16x32_bf16 v[118:121], v[168:171], v[184:187], v[118:121]
	v_mfma_f32_16x16x32_bf16 v[118:121], v[172:175], v[188:191], v[118:121]
	v_mfma_f32_16x16x32_bf16 v[114:117], v[176:179], v[184:187], v[114:117]
	v_mfma_f32_16x16x32_bf16 v[114:117], v[180:183], v[188:191], v[114:117]
	v_mfma_f32_16x16x32_bf16 v[102:105], v[168:171], v[192:195], v[102:105]
	v_mfma_f32_16x16x32_bf16 v[102:105], v[172:175], v[196:199], v[102:105]
	v_mfma_f32_16x16x32_bf16 v[98:101], v[176:179], v[192:195], v[98:101]
	v_mfma_f32_16x16x32_bf16 v[98:101], v[180:183], v[196:199], v[98:101]
	v_mfma_f32_16x16x32_bf16 v[86:89], v[168:171], v[200:203], v[86:89]
	v_mfma_f32_16x16x32_bf16 v[86:89], v[172:175], v[204:207], v[86:89]
	v_mfma_f32_16x16x32_bf16 v[82:85], v[176:179], v[200:203], v[82:85]
	v_mfma_f32_16x16x32_bf16 v[82:85], v[180:183], v[204:207], v[82:85]
	v_mfma_f32_16x16x32_bf16 v[70:73], v[168:171], v[208:211], v[70:73]
	v_mfma_f32_16x16x32_bf16 v[70:73], v[172:175], v[212:215], v[70:73]
	v_mfma_f32_16x16x32_bf16 v[66:69], v[176:179], v[208:211], v[66:69]
	v_mfma_f32_16x16x32_bf16 v[66:69], v[180:183], v[212:215], v[66:69]
	s_setprio 0
	s_barrier
	s_add_i32 s14, s35, s2
	v_lshl_add_u64 v[216:217], s[18:19], 0, v[134:135]
	s_mov_b32 m0, s14
	ds_read_b128 v[184:187], v154 offset:16384
	ds_read_b128 v[188:191], v154 offset:17408
	ds_read_b128 v[192:195], v154 offset:18432
	ds_read_b128 v[196:199], v154 offset:19456
	ds_read_b128 v[200:203], v154 offset:20480
	ds_read_b128 v[204:207], v154 offset:21504
	ds_read_b128 v[208:211], v154 offset:22528
	ds_read_b128 v[212:215], v154 offset:23552
	global_load_lds_dwordx4 v[216:217], off
	s_add_i32 m0, s14, 0x2000
	s_add_u32 s14, s18, 0x108000
	v_lshl_add_u64 v[218:219], s[18:19], 0, v[130:131]
	s_addc_u32 s15, s19, 0
	s_add_i32 s45, s36, s2
	global_load_lds_dwordx4 v[218:219], off
	v_lshl_add_u64 v[220:221], s[14:15], 0, v[134:135]
	s_mov_b32 m0, s45
	v_lshl_add_u64 v[222:223], s[20:21], 0, v[132:133]
	global_load_lds_dwordx4 v[220:221], off
	v_lshl_add_u64 v[220:221], s[14:15], 0, v[130:131]
	s_add_i32 m0, s45, 0x2000
	s_nop 0
	global_load_lds_dwordx4 v[220:221], off
	v_lshl_add_u64 v[220:221], s[20:21], 0, v[136:137]
	s_mov_b32 m0, s26
	s_nop 0
	global_load_lds_dwordx4 v[220:221], off
	s_mov_b32 m0, s27
	s_nop 0
	global_load_lds_dwordx4 v[222:223], off
	s_waitcnt vmcnt(8)
	s_waitcnt lgkmcnt(0)
	s_barrier
; #define PG8_STAGE(bufoff, gbase, voff) do { _Pragma("unroll") for (int _i = 0; _i < 2; ++_i) \
;         __builtin_amdgcn_global_load_lds((const unsigned*)((const char*)(gbase) + (voff)[_i]), (PG8_LAS unsigned*)(lds + (bufoff) + ldsw + _i * 8192), 16, 0, 0); } while (0)
; #define PG8_LDA(dst, b, h) do { _Pragma("unroll") for (int m = 0; m < 4; ++m) _Pragma("unroll") for (int k = 0; k < 2; ++k) dst[m][k] = *(const PG8_LAS bf16x8*)(lds + PG8_SA(b, h) + aoff + m * 2048 + k * 1024); } while (0)
; #define PG8_LDB(dst, b, h) do { _Pragma("unroll") for (int n = 0; n < 2; ++n) _Pragma("unroll") for (int k = 0; k < 2; ++k) dst[n][k] = *(const PG8_LAS bf16x8*)(lds + PG8_SB(b, h) + boff + n * 2048 + k * 1024); } while (0)
; #define PG8_MMA(ai, bj, At, Bt) do { __builtin_amdgcn_s_setprio(1); _Pragma("unroll") for (int m = 0; m < 4; ++m) _Pragma("unroll") for (int n = 0; n < 2; ++n) _Pragma("unroll") for (int k = 0; k < 2; ++k) \
;         acc[ai][bj][m][n] = __builtin_amdgcn_mfma_f32_16x16x32_bf16(Bt[n][k], At[m][k], acc[ai][bj][m][n], 0, 0, 0); __builtin_amdgcn_s_setprio(0); } while (0)
; #define PG8_WAIT_V(n) asm volatile("s_waitcnt vmcnt(" #n ")" ::: "memory")
; #define PG8_WAIT_L(n) asm volatile("s_waitcnt lgkmcnt(" #n ")" ::: "memory")
; #define PG8_BAR __builtin_amdgcn_s_barrier()
; #define PG8_SCHED __builtin_amdgcn_sched_barrier(0)
; template <class Epi, class Sched, bool ALIGN_EPI = false, bool SP2 = false>
; __device__ __forceinline__ void gemm_phase(PG8_LAS unsigned char* lds, const Gemm g, const Sched& S, const Epi& E) {
;     ...
;             PG8_WAIT_V(8); PG8_WAIT_L(0); PG8_BAR; PG8_MMA(1, 0, At, B0); PG8_MMA(1, 1, At, B1); PG8_BAR; PG8_SCHED;
;             PG8_LDB(B0, 1, 0); PG8_LDB(B1, 1, 1); PG8_SCHED; PG8_LDA(At, 1, 0); PG8_STAGE(PG8_SA(0, 1), a2 + hstep, voffA);
;             PG8_WAIT_V(8); PG8_WAIT_L(0); PG8_BAR; PG8_MMA(0, 0, At, B0); PG8_MMA(0, 1, At, B1); PG8_BAR; PG8_SCHED;
	s_setprio 1
	s_waitcnt lgkmcnt(0)
	v_mfma_f32_16x16x32_bf16 v[62:65], v[146:149], v[184:187], v[62:65]
	v_mfma_f32_16x16x32_bf16 v[62:65], v[156:159], v[188:191], v[62:65]
	v_mfma_f32_16x16x32_bf16 v[58:61], v[160:163], v[184:187], v[58:61]
	v_mfma_f32_16x16x32_bf16 v[58:61], v[164:167], v[188:191], v[58:61]
	v_mfma_f32_16x16x32_bf16 v[46:49], v[146:149], v[192:195], v[46:49]
	v_mfma_f32_16x16x32_bf16 v[46:49], v[156:159], v[196:199], v[46:49]
	v_mfma_f32_16x16x32_bf16 v[42:45], v[160:163], v[192:195], v[42:45]
	v_mfma_f32_16x16x32_bf16 v[42:45], v[164:167], v[196:199], v[42:45]
	v_mfma_f32_16x16x32_bf16 v[30:33], v[146:149], v[200:203], v[30:33]
	v_mfma_f32_16x16x32_bf16 v[30:33], v[156:159], v[204:207], v[30:33]
	v_mfma_f32_16x16x32_bf16 v[26:29], v[160:163], v[200:203], v[26:29]
	v_mfma_f32_16x16x32_bf16 v[26:29], v[164:167], v[204:207], v[26:29]
	v_mfma_f32_16x16x32_bf16 v[14:17], v[146:149], v[208:211], v[14:17]
	v_mfma_f32_16x16x32_bf16 v[14:17], v[156:159], v[212:215], v[14:17]
	v_mfma_f32_16x16x32_bf16 v[10:13], v[160:163], v[208:211], v[10:13]
	v_mfma_f32_16x16x32_bf16 v[10:13], v[164:167], v[212:215], v[10:13]
	v_mfma_f32_16x16x32_bf16 v[54:57], v[168:171], v[184:187], v[54:57]
	v_mfma_f32_16x16x32_bf16 v[54:57], v[172:175], v[188:191], v[54:57]
	v_mfma_f32_16x16x32_bf16 v[50:53], v[176:179], v[184:187], v[50:53]
	v_mfma_f32_16x16x32_bf16 v[50:53], v[180:183], v[188:191], v[50:53]
	v_mfma_f32_16x16x32_bf16 v[38:41], v[168:171], v[192:195], v[38:41]
	v_mfma_f32_16x16x32_bf16 v[38:41], v[172:175], v[196:199], v[38:41]
	v_mfma_f32_16x16x32_bf16 v[34:37], v[176:179], v[192:195], v[34:37]
	v_mfma_f32_16x16x32_bf16 v[34:37], v[180:183], v[196:199], v[34:37]
	v_mfma_f32_16x16x32_bf16 v[22:25], v[168:171], v[200:203], v[22:25]
	v_mfma_f32_16x16x32_bf16 v[22:25], v[172:175], v[204:207], v[22:25]
	v_mfma_f32_16x16x32_bf16 v[18:21], v[176:179], v[200:203], v[18:21]
	v_mfma_f32_16x16x32_bf16 v[18:21], v[180:183], v[204:207], v[18:21]
	v_mfma_f32_16x16x32_bf16 v[6:9], v[168:171], v[208:211], v[6:9]
	v_mfma_f32_16x16x32_bf16 v[6:9], v[172:175], v[212:215], v[6:9]
	v_mfma_f32_16x16x32_bf16 v[2:5], v[176:179], v[208:211], v[2:5]
	v_mfma_f32_16x16x32_bf16 v[2:5], v[180:183], v[212:215], v[2:5]
	s_setprio 0
	s_barrier
	s_add_i32 s45, 0, 0x18000
	v_add_u32_e32 v155, s45, v150
	s_add_i32 s46, 0, 0x1c000
	ds_read_b128 v[146:149], v155
	ds_read_b128 v[156:159], v155 offset:1024
	ds_read_b128 v[160:163], v155 offset:2048
	ds_read_b128 v[164:167], v155 offset:3072
	v_add_u32_e32 v155, s46, v150
	ds_read_b128 v[168:171], v155
	ds_read_b128 v[172:175], v155 offset:1024
	ds_read_b128 v[176:179], v155 offset:2048
	ds_read_b128 v[180:183], v155 offset:3072
	s_add_u32 s14, s20, 0x108000
	s_addc_u32 s15, s21, 0
	s_mov_b32 m0, s28
	v_lshl_add_u64 v[224:225], s[14:15], 0, v[136:137]
	ds_read_b128 v[184:187], v154 offset:32768
	ds_read_b128 v[188:191], v154 offset:33792
	ds_read_b128 v[192:195], v154 offset:34816
	ds_read_b128 v[196:199], v154 offset:35840
	ds_read_b128 v[200:203], v154 offset:36864
	ds_read_b128 v[204:207], v154 offset:37888
	ds_read_b128 v[208:211], v154 offset:38912
	ds_read_b128 v[212:215], v154 offset:39936
	global_load_lds_dwordx4 v[224:225], off
	v_lshl_add_u64 v[224:225], s[14:15], 0, v[132:133]
	s_mov_b32 m0, s29
	s_nop 0
	global_load_lds_dwordx4 v[224:225], off
	s_waitcnt vmcnt(8)
	s_waitcnt lgkmcnt(0)
	s_barrier
	s_setprio 1
	s_waitcnt lgkmcnt(0)
	v_mfma_f32_16x16x32_bf16 v[126:129], v[146:149], v[184:187], v[126:129]
	v_mfma_f32_16x16x32_bf16 v[126:129], v[156:159], v[188:191], v[126:129]
	v_mfma_f32_16x16x32_bf16 v[122:125], v[160:163], v[184:187], v[122:125]
	v_mfma_f32_16x16x32_bf16 v[122:125], v[164:167], v[188:191], v[122:125]
	v_mfma_f32_16x16x32_bf16 v[110:113], v[146:149], v[192:195], v[110:113]
	v_mfma_f32_16x16x32_bf16 v[110:113], v[156:159], v[196:199], v[110:113]
	v_mfma_f32_16x16x32_bf16 v[106:109], v[160:163], v[192:195], v[106:109]
	v_mfma_f32_16x16x32_bf16 v[106:109], v[164:167], v[196:199], v[106:109]
	v_mfma_f32_16x16x32_bf16 v[94:97], v[146:149], v[200:203], v[94:97]
	v_mfma_f32_16x16x32_bf16 v[94:97], v[156:159], v[204:207], v[94:97]
	v_mfma_f32_16x16x32_bf16 v[90:93], v[160:163], v[200:203], v[90:93]
	v_mfma_f32_16x16x32_bf16 v[90:93], v[164:167], v[204:207], v[90:93]
	v_mfma_f32_16x16x32_bf16 v[78:81], v[146:149], v[208:211], v[78:81]
	v_mfma_f32_16x16x32_bf16 v[78:81], v[156:159], v[212:215], v[78:81]
	v_mfma_f32_16x16x32_bf16 v[74:77], v[160:163], v[208:211], v[74:77]
	v_mfma_f32_16x16x32_bf16 v[74:77], v[164:167], v[212:215], v[74:77]
	v_mfma_f32_16x16x32_bf16 v[118:121], v[168:171], v[184:187], v[118:121]
	v_mfma_f32_16x16x32_bf16 v[118:121], v[172:175], v[188:191], v[118:121]
	v_mfma_f32_16x16x32_bf16 v[114:117], v[176:179], v[184:187], v[114:117]
	v_mfma_f32_16x16x32_bf16 v[114:117], v[180:183], v[188:191], v[114:117]
	v_mfma_f32_16x16x32_bf16 v[102:105], v[168:171], v[192:195], v[102:105]
	v_mfma_f32_16x16x32_bf16 v[102:105], v[172:175], v[196:199], v[102:105]
	v_mfma_f32_16x16x32_bf16 v[98:101], v[176:179], v[192:195], v[98:101]
	v_mfma_f32_16x16x32_bf16 v[98:101], v[180:183], v[196:199], v[98:101]
	v_mfma_f32_16x16x32_bf16 v[86:89], v[168:171], v[200:203], v[86:89]
	v_mfma_f32_16x16x32_bf16 v[86:89], v[172:175], v[204:207], v[86:89]
	v_mfma_f32_16x16x32_bf16 v[82:85], v[176:179], v[200:203], v[82:85]
	v_mfma_f32_16x16x32_bf16 v[82:85], v[180:183], v[204:207], v[82:85]
	v_mfma_f32_16x16x32_bf16 v[70:73], v[168:171], v[208:211], v[70:73]
	v_mfma_f32_16x16x32_bf16 v[70:73], v[172:175], v[212:215], v[70:73]
	v_mfma_f32_16x16x32_bf16 v[66:69], v[176:179], v[208:211], v[66:69]
	v_mfma_f32_16x16x32_bf16 v[66:69], v[180:183], v[212:215], v[66:69]
	s_setprio 0
	s_barrier
; #define PG8_STAGE(bufoff, gbase, voff) do { _Pragma("unroll") for (int _i = 0; _i < 2; ++_i) \
;         __builtin_amdgcn_global_load_lds((const unsigned*)((const char*)(gbase) + (voff)[_i]), (PG8_LAS unsigned*)(lds + (bufoff) + ldsw + _i * 8192), 16, 0, 0); } while (0)
; #define PG8_LDA(dst, b, h) do { _Pragma("unroll") for (int m = 0; m < 4; ++m) _Pragma("unroll") for (int k = 0; k < 2; ++k) dst[m][k] = *(const PG8_LAS bf16x8*)(lds + PG8_SA(b, h) + aoff + m * 2048 + k * 1024); } while (0)
; #define PG8_WAIT_V(n) asm volatile("s_waitcnt vmcnt(" #n ")" ::: "memory")
; template <class Epi, class Sched, bool ALIGN_EPI = false, bool SP2 = false>
; __device__ __forceinline__ void gemm_phase(PG8_LAS unsigned char* lds, const Gemm g, const Sched& S, const Epi& E) {
;     ...
;             PG8_LDA(At, 1, 1); PG8_STAGE(PG8_SB(1, 0), b3, voffB); PG8_STAGE(PG8_SB(1, 1), b3 + hstepB, voffB); PG8_STAGE(PG8_SA(1, 0), a3, voffA);
;             PG8_WAIT_V(8); PG8_WAIT_L(0); PG8_BAR; PG8_MMA(1, 0, At, B0); PG8_MMA(1, 1, At, B1); PG8_BAR; PG8_SCHED;
;             } else {
;             PG8_LDB(B0, 0, 0); PG8_SCHED; PG8_LDA(At, 0, 0); PG8_STAGE(PG8_SA(1, 1), a1 + hstep, voffA);
;             PG8_WAIT_L(8); PG8_BAR; PG8_WAIT_L(0); PG8_MMA(0, 0, At, B0); PG8_BAR; PG8_SCHED;
;             PG8_LDB(B1, 0, 1); PG8_STAGE(PG8_SB(0, 0), b2, voffB);
;             PG8_BAR; PG8_WAIT_L(0); PG8_MMA(0, 1, At, B1); PG8_BAR;
;             PG8_LDA(At, 0, 1); PG8_STAGE(PG8_SA(0, 0), a2, voffA);
;             PG8_BAR; PG8_WAIT_L(0); PG8_MMA(1, 0, At, B0); PG8_BAR; PG8_SCHED;
;             PG8_STAGE(PG8_SB(0, 1), b2 + hstepB, voffB);
;             PG8_WAIT_V(6); PG8_BAR; PG8_MMA(1, 1, At, B1); PG8_BAR;
;             PG8_LDB(B0, 1, 0); PG8_SCHED; PG8_LDA(At, 1, 0); PG8_STAGE(PG8_SA(0, 1), a2 + hstep, voffA);
;             PG8_WAIT_L(8); PG8_BAR; PG8_WAIT_L(0); PG8_MMA(0, 0, At, B0); PG8_BAR; PG8_SCHED;
;             PG8_LDB(B1, 1, 1); PG8_STAGE(PG8_SB(1, 0), b3, voffB);
;             PG8_BAR; PG8_WAIT_L(0); PG8_MMA(0, 1, At, B1); PG8_BAR;
;             PG8_LDA(At, 1, 1); PG8_STAGE(PG8_SA(1, 0), a3, voffA);
;             PG8_BAR; PG8_WAIT_L(0); PG8_MMA(1, 0, At, B0); PG8_BAR; PG8_SCHED;
;             PG8_STAGE(PG8_SB(1, 1), b3 + hstepB, voffB);
;             PG8_WAIT_V(6); PG8_BAR; PG8_MMA(1, 1, At, B1); PG8_BAR;
;             }
;         }
;         if constexpr (ALIGN_EPI) { if (wr == 0) PG8_BAR; }
	s_add_i32 s14, s45, s2
	v_lshl_add_u64 v[216:217], v[216:217], 0, s[8:9]
	s_mov_b32 m0, s14
	ds_read_b128 v[184:187], v154 offset:49152
	ds_read_b128 v[188:191], v154 offset:50176
	ds_read_b128 v[192:195], v154 offset:51200
	ds_read_b128 v[196:199], v154 offset:52224
	ds_read_b128 v[200:203], v154 offset:53248
	ds_read_b128 v[204:207], v154 offset:54272
	ds_read_b128 v[208:211], v154 offset:55296
	ds_read_b128 v[212:215], v154 offset:56320
	global_load_lds_dwordx4 v[216:217], off
	s_add_i32 m0, s14, 0x2000
	s_add_u32 s14, s18, 0x108080
	v_lshl_add_u64 v[216:217], v[218:219], 0, s[8:9]
	s_addc_u32 s15, s19, 0
	s_add_i32 s18, s46, s2
	global_load_lds_dwordx4 v[216:217], off
	v_lshl_add_u64 v[216:217], s[14:15], 0, v[134:135]
	s_mov_b32 m0, s18
	s_nop 0
	global_load_lds_dwordx4 v[216:217], off
	v_lshl_add_u64 v[216:217], s[14:15], 0, v[130:131]
	s_add_i32 m0, s18, 0x2000
	s_nop 0
	global_load_lds_dwordx4 v[216:217], off
	v_lshl_add_u64 v[216:217], v[220:221], 0, s[8:9]
	s_mov_b32 m0, s31
	s_nop 0
	global_load_lds_dwordx4 v[216:217], off
	v_lshl_add_u64 v[216:217], v[222:223], 0, s[8:9]
	s_mov_b32 m0, s33
	s_nop 0
	global_load_lds_dwordx4 v[216:217], off
	s_waitcnt vmcnt(8)
	s_waitcnt lgkmcnt(0)
	s_barrier
	s_setprio 1
	s_waitcnt lgkmcnt(0)
	v_mfma_f32_16x16x32_bf16 v[62:65], v[146:149], v[184:187], v[62:65]
	v_mfma_f32_16x16x32_bf16 v[62:65], v[156:159], v[188:191], v[62:65]
	v_mfma_f32_16x16x32_bf16 v[58:61], v[160:163], v[184:187], v[58:61]
	v_mfma_f32_16x16x32_bf16 v[58:61], v[164:167], v[188:191], v[58:61]
	v_mfma_f32_16x16x32_bf16 v[46:49], v[146:149], v[192:195], v[46:49]
	v_mfma_f32_16x16x32_bf16 v[46:49], v[156:159], v[196:199], v[46:49]
	v_mfma_f32_16x16x32_bf16 v[42:45], v[160:163], v[192:195], v[42:45]
	v_mfma_f32_16x16x32_bf16 v[42:45], v[164:167], v[196:199], v[42:45]
	v_mfma_f32_16x16x32_bf16 v[30:33], v[146:149], v[200:203], v[30:33]
	v_mfma_f32_16x16x32_bf16 v[30:33], v[156:159], v[204:207], v[30:33]
	v_mfma_f32_16x16x32_bf16 v[26:29], v[160:163], v[200:203], v[26:29]
	v_mfma_f32_16x16x32_bf16 v[26:29], v[164:167], v[204:207], v[26:29]
	v_mfma_f32_16x16x32_bf16 v[14:17], v[146:149], v[208:211], v[14:17]
	v_mfma_f32_16x16x32_bf16 v[14:17], v[156:159], v[212:215], v[14:17]
	v_mfma_f32_16x16x32_bf16 v[10:13], v[160:163], v[208:211], v[10:13]
	v_mfma_f32_16x16x32_bf16 v[10:13], v[164:167], v[212:215], v[10:13]
	v_mfma_f32_16x16x32_bf16 v[54:57], v[168:171], v[184:187], v[54:57]
	v_mfma_f32_16x16x32_bf16 v[54:57], v[172:175], v[188:191], v[54:57]
	v_mfma_f32_16x16x32_bf16 v[50:53], v[176:179], v[184:187], v[50:53]
	v_mfma_f32_16x16x32_bf16 v[50:53], v[180:183], v[188:191], v[50:53]
	v_mfma_f32_16x16x32_bf16 v[38:41], v[168:171], v[192:195], v[38:41]
	v_mfma_f32_16x16x32_bf16 v[38:41], v[172:175], v[196:199], v[38:41]
	v_mfma_f32_16x16x32_bf16 v[34:37], v[176:179], v[192:195], v[34:37]
	v_mfma_f32_16x16x32_bf16 v[34:37], v[180:183], v[196:199], v[34:37]
	v_mfma_f32_16x16x32_bf16 v[22:25], v[168:171], v[200:203], v[22:25]
	v_mfma_f32_16x16x32_bf16 v[22:25], v[172:175], v[204:207], v[22:25]
	v_mfma_f32_16x16x32_bf16 v[18:21], v[176:179], v[200:203], v[18:21]
	v_mfma_f32_16x16x32_bf16 v[18:21], v[180:183], v[204:207], v[18:21]
	v_mfma_f32_16x16x32_bf16 v[6:9], v[168:171], v[208:211], v[6:9]
	v_mfma_f32_16x16x32_bf16 v[6:9], v[172:175], v[212:215], v[6:9]
	v_mfma_f32_16x16x32_bf16 v[2:5], v[176:179], v[208:211], v[2:5]
	v_mfma_f32_16x16x32_bf16 v[2:5], v[180:183], v[212:215], v[2:5]
	s_setprio 0
	s_barrier
	s_add_i32 s44, s44, 2
	s_add_u32 s42, s42, 0x100
	s_addc_u32 s43, s43, 0
	s_cmp_gt_u32 s44, 61
	s_mov_b64 s[14:15], s[16:17]
	s_cbranch_scc0 .LBB0_1889
	s_and_b64 vcc, exec, s[10:11]
	s_cbranch_vccz .LBB0_1892
	s_barrier

; #define PG8_STAGE(bufoff, gbase, voff) do { _Pragma("unroll") for (int _i = 0; _i < 2; ++_i) \
;         __builtin_amdgcn_global_load_lds((const unsigned*)((const char*)(gbase) + (voff)[_i]), (PG8_LAS unsigned*)(lds + (bufoff) + ldsw + _i * 8192), 16, 0, 0); } while (0)
; #define PG8_LDA(dst, b, h) do { _Pragma("unroll") for (int m = 0; m < 4; ++m) _Pragma("unroll") for (int k = 0; k < 2; ++k) dst[m][k] = *(const PG8_LAS bf16x8*)(lds + PG8_SA(b, h) + aoff + m * 2048 + k * 1024); } while (0)
; #define PG8_LDB(dst, b, h) do { _Pragma("unroll") for (int n = 0; n < 2; ++n) _Pragma("unroll") for (int k = 0; k < 2; ++k) dst[n][k] = *(const PG8_LAS bf16x8*)(lds + PG8_SB(b, h) + boff + n * 2048 + k * 1024); } while (0)
; #define PG8_MMA(ai, bj, At, Bt) do { __builtin_amdgcn_s_setprio(1); _Pragma("unroll") for (int m = 0; m < 4; ++m) _Pragma("unroll") for (int n = 0; n < 2; ++n) _Pragma("unroll") for (int k = 0; k < 2; ++k) \
;         acc[ai][bj][m][n] = __builtin_amdgcn_mfma_f32_16x16x32_bf16(Bt[n][k], At[m][k], acc[ai][bj][m][n], 0, 0, 0); __builtin_amdgcn_s_setprio(0); } while (0)
; #define PG8_WAIT_V(n) asm volatile("s_waitcnt vmcnt(" #n ")" ::: "memory")
; #define PG8_BAR __builtin_amdgcn_s_barrier()
; template <class Epi, class Sched, bool ALIGN_EPI = false, bool SP2 = false>
; __device__ __forceinline__ void gemm_phase(PG8_LAS unsigned char* lds, const Gemm g, const Sched& S, const Epi& E) {
;     ...
;         for (int t = 0; t < nt; t += 2) {
;             const bool last = (t == nt - 2);
;             const char* a1 = cA + (size_t)(t + 1) * kstep;
;             const char* a2 = last ? nA : cA + (size_t)(t + 2) * kstep; const char* b2 = last ? nB : cB + (size_t)(t + 2) * kstep;
;             const char* a3 = a2 + kstep; const char* b3 = b2 + kstep;
;             if (last && has_next) S.a_ready(nxt);
;             if constexpr (SP2) {
;             PG8_LDB(B0, 0, 0); PG8_LDB(B1, 0, 1); PG8_SCHED; PG8_LDA(At, 0, 0); PG8_STAGE(PG8_SA(1, 1), a1 + hstep, voffA);
;             PG8_WAIT_V(8); PG8_WAIT_L(0); PG8_BAR; PG8_MMA(0, 0, At, B0); PG8_MMA(0, 1, At, B1); PG8_BAR; PG8_SCHED;
;             PG8_LDA(At, 0, 1); PG8_STAGE(PG8_SB(0, 0), b2, voffB); PG8_STAGE(PG8_SB(0, 1), b2 + hstepB, voffB); PG8_STAGE(PG8_SA(0, 0), a2, voffA);
;             PG8_WAIT_V(8); PG8_WAIT_L(0); PG8_BAR; PG8_MMA(1, 0, At, B0); PG8_MMA(1, 1, At, B1); PG8_BAR; PG8_SCHED;
.LBB0_2165:
	ds_read_b128 v[128:131], v167
	ds_read_b128 v[132:135], v167 offset:1024
	ds_read_b128 v[136:139], v167 offset:2048
	ds_read_b128 v[140:143], v167 offset:3072
	ds_read_b128 v[160:163], v168
	ds_read_b128 v[170:173], v168 offset:1024
	ds_read_b128 v[174:177], v168 offset:2048
	ds_read_b128 v[178:181], v168 offset:3072
	s_add_u32 s16, s14, 0x100
	s_addc_u32 s17, s15, 0
	s_cmpk_eq_i32 s57, 0xa8
	s_cselect_b32 s21, s5, s17
	s_cselect_b32 s20, s4, s16
	s_cselect_b32 s19, s13, s56
	s_cselect_b32 s18, s12, s55
	v_lshl_add_u64 v[214:215], s[14:15], 0, v[152:153]
	s_add_i32 m0, s25, 0xc000
	ds_read_b128 v[182:185], v169
	ds_read_b128 v[186:189], v169 offset:1024
	ds_read_b128 v[190:193], v169 offset:2048
	ds_read_b128 v[194:197], v169 offset:3072
	ds_read_b128 v[198:201], v169 offset:4096
	ds_read_b128 v[202:205], v169 offset:5120
	ds_read_b128 v[206:209], v169 offset:6144
	ds_read_b128 v[210:213], v169 offset:7168
	global_load_lds_dwordx4 v[214:215], off
	v_lshl_add_u64 v[214:215], s[14:15], 0, v[154:155]
	s_add_i32 m0, s25, 0xe000
	s_nop 0
	global_load_lds_dwordx4 v[214:215], off
	s_waitcnt vmcnt(8)
	s_waitcnt lgkmcnt(0)
	s_barrier
	s_setprio 1
	s_waitcnt lgkmcnt(0)
	v_mfma_f32_16x16x32_bf16 v[124:127], v[128:131], v[182:185], v[124:127]
	v_mfma_f32_16x16x32_bf16 v[124:127], v[132:135], v[186:189], v[124:127]
	v_mfma_f32_16x16x32_bf16 v[120:123], v[136:139], v[182:185], v[120:123]
	v_mfma_f32_16x16x32_bf16 v[120:123], v[140:143], v[186:189], v[120:123]
	v_mfma_f32_16x16x32_bf16 v[116:119], v[128:131], v[190:193], v[116:119]
	v_mfma_f32_16x16x32_bf16 v[116:119], v[132:135], v[194:197], v[116:119]
	v_mfma_f32_16x16x32_bf16 v[108:111], v[136:139], v[190:193], v[108:111]
	v_mfma_f32_16x16x32_bf16 v[108:111], v[140:143], v[194:197], v[108:111]
	v_mfma_f32_16x16x32_bf16 v[92:95], v[128:131], v[198:201], v[92:95]
	v_mfma_f32_16x16x32_bf16 v[92:95], v[132:135], v[202:205], v[92:95]
	v_mfma_f32_16x16x32_bf16 v[88:91], v[136:139], v[198:201], v[88:91]
	v_mfma_f32_16x16x32_bf16 v[88:91], v[140:143], v[202:205], v[88:91]
	v_mfma_f32_16x16x32_bf16 v[80:83], v[128:131], v[206:209], v[80:83]
	v_mfma_f32_16x16x32_bf16 v[80:83], v[132:135], v[210:213], v[80:83]
	v_mfma_f32_16x16x32_bf16 v[72:75], v[136:139], v[206:209], v[72:75]
	v_mfma_f32_16x16x32_bf16 v[72:75], v[140:143], v[210:213], v[72:75]
	v_mfma_f32_16x16x32_bf16 v[112:115], v[160:163], v[182:185], v[112:115]
	v_mfma_f32_16x16x32_bf16 v[112:115], v[170:173], v[186:189], v[112:115]
	v_mfma_f32_16x16x32_bf16 v[104:107], v[174:177], v[182:185], v[104:107]
	v_mfma_f32_16x16x32_bf16 v[104:107], v[178:181], v[186:189], v[104:107]
	v_mfma_f32_16x16x32_bf16 v[100:103], v[160:163], v[190:193], v[100:103]
	v_mfma_f32_16x16x32_bf16 v[100:103], v[170:173], v[194:197], v[100:103]
	v_mfma_f32_16x16x32_bf16 v[96:99], v[174:177], v[190:193], v[96:99]
	v_mfma_f32_16x16x32_bf16 v[96:99], v[178:181], v[194:197], v[96:99]
	v_mfma_f32_16x16x32_bf16 v[84:87], v[160:163], v[198:201], v[84:87]
	v_mfma_f32_16x16x32_bf16 v[84:87], v[170:173], v[202:205], v[84:87]
	v_mfma_f32_16x16x32_bf16 v[76:79], v[174:177], v[198:201], v[76:79]
	v_mfma_f32_16x16x32_bf16 v[76:79], v[178:181], v[202:205], v[76:79]
	v_mfma_f32_16x16x32_bf16 v[68:71], v[160:163], v[206:209], v[68:71]
	v_mfma_f32_16x16x32_bf16 v[68:71], v[170:173], v[210:213], v[68:71]
	v_mfma_f32_16x16x32_bf16 v[64:67], v[174:177], v[206:209], v[64:67]
	v_mfma_f32_16x16x32_bf16 v[64:67], v[178:181], v[210:213], v[64:67]
	s_setprio 0
	s_barrier
	s_add_i32 s14, s36, s24
	v_lshl_add_u64 v[214:215], s[18:19], 0, v[146:147]
	s_mov_b32 m0, s14
	ds_read_b128 v[182:185], v169 offset:16384
	ds_read_b128 v[186:189], v169 offset:17408
	ds_read_b128 v[190:193], v169 offset:18432
	ds_read_b128 v[194:197], v169 offset:19456
	ds_read_b128 v[198:201], v169 offset:20480
	ds_read_b128 v[202:205], v169 offset:21504
	ds_read_b128 v[206:209], v169 offset:22528
	ds_read_b128 v[210:213], v169 offset:23552
	global_load_lds_dwordx4 v[214:215], off
	s_add_i32 m0, s14, 0x2000
	s_add_u32 s14, s18, 0x2b0000
	v_lshl_add_u64 v[216:217], s[18:19], 0, v[150:151]
	s_addc_u32 s15, s19, 0
	s_add_i32 s58, s37, s24
	global_load_lds_dwordx4 v[216:217], off
	v_lshl_add_u64 v[218:219], s[14:15], 0, v[146:147]
	s_mov_b32 m0, s58
	v_lshl_add_u64 v[220:221], s[20:21], 0, v[148:149]
	global_load_lds_dwordx4 v[218:219], off
	v_lshl_add_u64 v[218:219], s[14:15], 0, v[150:151]
	s_add_i32 m0, s58, 0x2000
	s_nop 0
	global_load_lds_dwordx4 v[218:219], off
	v_lshl_add_u64 v[218:219], s[20:21], 0, v[144:145]
	s_mov_b32 m0, s25
	s_nop 0
	global_load_lds_dwordx4 v[218:219], off
	s_mov_b32 m0, s26
	s_nop 0
	global_load_lds_dwordx4 v[220:221], off
	s_waitcnt vmcnt(8)
	s_waitcnt lgkmcnt(0)
	s_barrier
; #define PG8_STAGE(bufoff, gbase, voff) do { _Pragma("unroll") for (int _i = 0; _i < 2; ++_i) \
;         __builtin_amdgcn_global_load_lds((const unsigned*)((const char*)(gbase) + (voff)[_i]), (PG8_LAS unsigned*)(lds + (bufoff) + ldsw + _i * 8192), 16, 0, 0); } while (0)
; #define PG8_LDA(dst, b, h) do { _Pragma("unroll") for (int m = 0; m < 4; ++m) _Pragma("unroll") for (int k = 0; k < 2; ++k) dst[m][k] = *(const PG8_LAS bf16x8*)(lds + PG8_SA(b, h) + aoff + m * 2048 + k * 1024); } while (0)
; #define PG8_LDB(dst, b, h) do { _Pragma("unroll") for (int n = 0; n < 2; ++n) _Pragma("unroll") for (int k = 0; k < 2; ++k) dst[n][k] = *(const PG8_LAS bf16x8*)(lds + PG8_SB(b, h) + boff + n * 2048 + k * 1024); } while (0)
; #define PG8_MMA(ai, bj, At, Bt) do { __builtin_amdgcn_s_setprio(1); _Pragma("unroll") for (int m = 0; m < 4; ++m) _Pragma("unroll") for (int n = 0; n < 2; ++n) _Pragma("unroll") for (int k = 0; k < 2; ++k) \
;         acc[ai][bj][m][n] = __builtin_amdgcn_mfma_f32_16x16x32_bf16(Bt[n][k], At[m][k], acc[ai][bj][m][n], 0, 0, 0); __builtin_amdgcn_s_setprio(0); } while (0)
; #define PG8_WAIT_V(n) asm volatile("s_waitcnt vmcnt(" #n ")" ::: "memory")
; #define PG8_WAIT_L(n) asm volatile("s_waitcnt lgkmcnt(" #n ")" ::: "memory")
; #define PG8_BAR __builtin_amdgcn_s_barrier()
; #define PG8_SCHED __builtin_amdgcn_sched_barrier(0)
; template <class Epi, class Sched, bool ALIGN_EPI = false, bool SP2 = false>
; __device__ __forceinline__ void gemm_phase(PG8_LAS unsigned char* lds, const Gemm g, const Sched& S, const Epi& E) {
;     ...
;             PG8_WAIT_V(8); PG8_WAIT_L(0); PG8_BAR; PG8_MMA(1, 0, At, B0); PG8_MMA(1, 1, At, B1); PG8_BAR; PG8_SCHED;
;             PG8_LDB(B0, 1, 0); PG8_LDB(B1, 1, 1); PG8_SCHED; PG8_LDA(At, 1, 0); PG8_STAGE(PG8_SA(0, 1), a2 + hstep, voffA);
;             PG8_WAIT_V(8); PG8_WAIT_L(0); PG8_BAR; PG8_MMA(0, 0, At, B0); PG8_MMA(0, 1, At, B1); PG8_BAR; PG8_SCHED;
	s_setprio 1
	s_waitcnt lgkmcnt(0)
	v_mfma_f32_16x16x32_bf16 v[60:63], v[128:131], v[182:185], v[60:63]
	v_mfma_f32_16x16x32_bf16 v[60:63], v[132:135], v[186:189], v[60:63]
	v_mfma_f32_16x16x32_bf16 v[56:59], v[136:139], v[182:185], v[56:59]
	v_mfma_f32_16x16x32_bf16 v[56:59], v[140:143], v[186:189], v[56:59]
	v_mfma_f32_16x16x32_bf16 v[48:51], v[128:131], v[190:193], v[48:51]
	v_mfma_f32_16x16x32_bf16 v[48:51], v[132:135], v[194:197], v[48:51]
	v_mfma_f32_16x16x32_bf16 v[40:43], v[136:139], v[190:193], v[40:43]
	v_mfma_f32_16x16x32_bf16 v[40:43], v[140:143], v[194:197], v[40:43]
	v_mfma_f32_16x16x32_bf16 v[28:31], v[128:131], v[198:201], v[28:31]
	v_mfma_f32_16x16x32_bf16 v[28:31], v[132:135], v[202:205], v[28:31]
	v_mfma_f32_16x16x32_bf16 v[24:27], v[136:139], v[198:201], v[24:27]
	v_mfma_f32_16x16x32_bf16 v[24:27], v[140:143], v[202:205], v[24:27]
	v_mfma_f32_16x16x32_bf16 v[20:23], v[128:131], v[206:209], v[20:23]
	v_mfma_f32_16x16x32_bf16 v[20:23], v[132:135], v[210:213], v[20:23]
	v_mfma_f32_16x16x32_bf16 v[12:15], v[136:139], v[206:209], v[12:15]
	v_mfma_f32_16x16x32_bf16 v[12:15], v[140:143], v[210:213], v[12:15]
	v_mfma_f32_16x16x32_bf16 v[52:55], v[160:163], v[182:185], v[52:55]
	v_mfma_f32_16x16x32_bf16 v[52:55], v[170:173], v[186:189], v[52:55]
	v_mfma_f32_16x16x32_bf16 v[44:47], v[174:177], v[182:185], v[44:47]
	v_mfma_f32_16x16x32_bf16 v[44:47], v[178:181], v[186:189], v[44:47]
	v_mfma_f32_16x16x32_bf16 v[36:39], v[160:163], v[190:193], v[36:39]
	v_mfma_f32_16x16x32_bf16 v[36:39], v[170:173], v[194:197], v[36:39]
	v_mfma_f32_16x16x32_bf16 v[32:35], v[174:177], v[190:193], v[32:35]
	v_mfma_f32_16x16x32_bf16 v[32:35], v[178:181], v[194:197], v[32:35]
	v_mfma_f32_16x16x32_bf16 v[16:19], v[160:163], v[198:201], v[16:19]
	v_mfma_f32_16x16x32_bf16 v[16:19], v[170:173], v[202:205], v[16:19]
	v_mfma_f32_16x16x32_bf16 v[8:11], v[174:177], v[198:201], v[8:11]
	v_mfma_f32_16x16x32_bf16 v[8:11], v[178:181], v[202:205], v[8:11]
	v_mfma_f32_16x16x32_bf16 v[4:7], v[160:163], v[206:209], v[4:7]
	v_mfma_f32_16x16x32_bf16 v[4:7], v[170:173], v[210:213], v[4:7]
	v_mfma_f32_16x16x32_bf16 v[0:3], v[174:177], v[206:209], v[0:3]
	v_mfma_f32_16x16x32_bf16 v[0:3], v[178:181], v[210:213], v[0:3]
	s_setprio 0
	s_barrier
	s_add_i32 s58, 0, 0x18000
	s_add_i32 s59, 0, 0x1c000
	v_add_u32_e32 v140, s58, v165
	v_add_u32_e32 v178, s59, v165
	ds_read_b128 v[128:131], v140
	ds_read_b128 v[132:135], v140 offset:1024
	ds_read_b128 v[136:139], v140 offset:2048
	ds_read_b128 v[140:143], v140 offset:3072
	ds_read_b128 v[160:163], v178
	ds_read_b128 v[170:173], v178 offset:1024
	ds_read_b128 v[174:177], v178 offset:2048
	ds_read_b128 v[178:181], v178 offset:3072
	s_add_u32 s14, s20, 0x2b0000
	s_addc_u32 s15, s21, 0
	s_mov_b32 m0, s27
	v_lshl_add_u64 v[222:223], s[14:15], 0, v[144:145]
	ds_read_b128 v[182:185], v169 offset:32768
	ds_read_b128 v[186:189], v169 offset:33792
	ds_read_b128 v[190:193], v169 offset:34816
	ds_read_b128 v[194:197], v169 offset:35840
	ds_read_b128 v[198:201], v169 offset:36864
	ds_read_b128 v[202:205], v169 offset:37888
	ds_read_b128 v[206:209], v169 offset:38912
	ds_read_b128 v[210:213], v169 offset:39936
	global_load_lds_dwordx4 v[222:223], off
	v_lshl_add_u64 v[222:223], s[14:15], 0, v[148:149]
	s_mov_b32 m0, s28
	s_nop 0
	global_load_lds_dwordx4 v[222:223], off
	s_waitcnt vmcnt(8)
	s_waitcnt lgkmcnt(0)
	s_barrier
	s_setprio 1
	s_waitcnt lgkmcnt(0)
	v_mfma_f32_16x16x32_bf16 v[124:127], v[128:131], v[182:185], v[124:127]
	v_mfma_f32_16x16x32_bf16 v[124:127], v[132:135], v[186:189], v[124:127]
	v_mfma_f32_16x16x32_bf16 v[120:123], v[136:139], v[182:185], v[120:123]
	v_mfma_f32_16x16x32_bf16 v[120:123], v[140:143], v[186:189], v[120:123]
	v_mfma_f32_16x16x32_bf16 v[116:119], v[128:131], v[190:193], v[116:119]
	v_mfma_f32_16x16x32_bf16 v[116:119], v[132:135], v[194:197], v[116:119]
	v_mfma_f32_16x16x32_bf16 v[108:111], v[136:139], v[190:193], v[108:111]
	v_mfma_f32_16x16x32_bf16 v[108:111], v[140:143], v[194:197], v[108:111]
	v_mfma_f32_16x16x32_bf16 v[92:95], v[128:131], v[198:201], v[92:95]
	v_mfma_f32_16x16x32_bf16 v[92:95], v[132:135], v[202:205], v[92:95]
	v_mfma_f32_16x16x32_bf16 v[88:91], v[136:139], v[198:201], v[88:91]
	v_mfma_f32_16x16x32_bf16 v[88:91], v[140:143], v[202:205], v[88:91]
	v_mfma_f32_16x16x32_bf16 v[80:83], v[128:131], v[206:209], v[80:83]
	v_mfma_f32_16x16x32_bf16 v[80:83], v[132:135], v[210:213], v[80:83]
	v_mfma_f32_16x16x32_bf16 v[72:75], v[136:139], v[206:209], v[72:75]
	v_mfma_f32_16x16x32_bf16 v[72:75], v[140:143], v[210:213], v[72:75]
	v_mfma_f32_16x16x32_bf16 v[112:115], v[160:163], v[182:185], v[112:115]
	v_mfma_f32_16x16x32_bf16 v[112:115], v[170:173], v[186:189], v[112:115]
	v_mfma_f32_16x16x32_bf16 v[104:107], v[174:177], v[182:185], v[104:107]
	v_mfma_f32_16x16x32_bf16 v[104:107], v[178:181], v[186:189], v[104:107]
	v_mfma_f32_16x16x32_bf16 v[100:103], v[160:163], v[190:193], v[100:103]
	v_mfma_f32_16x16x32_bf16 v[100:103], v[170:173], v[194:197], v[100:103]
	v_mfma_f32_16x16x32_bf16 v[96:99], v[174:177], v[190:193], v[96:99]
	v_mfma_f32_16x16x32_bf16 v[96:99], v[178:181], v[194:197], v[96:99]
	v_mfma_f32_16x16x32_bf16 v[84:87], v[160:163], v[198:201], v[84:87]
	v_mfma_f32_16x16x32_bf16 v[84:87], v[170:173], v[202:205], v[84:87]
	v_mfma_f32_16x16x32_bf16 v[76:79], v[174:177], v[198:201], v[76:79]
	v_mfma_f32_16x16x32_bf16 v[76:79], v[178:181], v[202:205], v[76:79]
	v_mfma_f32_16x16x32_bf16 v[68:71], v[160:163], v[206:209], v[68:71]
	v_mfma_f32_16x16x32_bf16 v[68:71], v[170:173], v[210:213], v[68:71]
	v_mfma_f32_16x16x32_bf16 v[64:67], v[174:177], v[206:209], v[64:67]
	v_mfma_f32_16x16x32_bf16 v[64:67], v[178:181], v[210:213], v[64:67]
	s_setprio 0
	s_barrier
; #define PG8_STAGE(bufoff, gbase, voff) do { _Pragma("unroll") for (int _i = 0; _i < 2; ++_i) \
;         __builtin_amdgcn_global_load_lds((const unsigned*)((const char*)(gbase) + (voff)[_i]), (PG8_LAS unsigned*)(lds + (bufoff) + ldsw + _i * 8192), 16, 0, 0); } while (0)
; #define PG8_LDA(dst, b, h) do { _Pragma("unroll") for (int m = 0; m < 4; ++m) _Pragma("unroll") for (int k = 0; k < 2; ++k) dst[m][k] = *(const PG8_LAS bf16x8*)(lds + PG8_SA(b, h) + aoff + m * 2048 + k * 1024); } while (0)
; #define PG8_WAIT_V(n) asm volatile("s_waitcnt vmcnt(" #n ")" ::: "memory")
; template <class Epi, class Sched, bool ALIGN_EPI = false, bool SP2 = false>
; __device__ __forceinline__ void gemm_phase(PG8_LAS unsigned char* lds, const Gemm g, const Sched& S, const Epi& E) {
;     ...
;             PG8_LDA(At, 1, 1); PG8_STAGE(PG8_SB(1, 0), b3, voffB); PG8_STAGE(PG8_SB(1, 1), b3 + hstepB, voffB); PG8_STAGE(PG8_SA(1, 0), a3, voffA);
;             PG8_WAIT_V(8); PG8_WAIT_L(0); PG8_BAR; PG8_MMA(1, 0, At, B0); PG8_MMA(1, 1, At, B1); PG8_BAR; PG8_SCHED;
;             } else {
;             PG8_LDB(B0, 0, 0); PG8_SCHED; PG8_LDA(At, 0, 0); PG8_STAGE(PG8_SA(1, 1), a1 + hstep, voffA);
;             PG8_WAIT_L(8); PG8_BAR; PG8_WAIT_L(0); PG8_MMA(0, 0, At, B0); PG8_BAR; PG8_SCHED;
;             PG8_LDB(B1, 0, 1); PG8_STAGE(PG8_SB(0, 0), b2, voffB);
;             PG8_BAR; PG8_WAIT_L(0); PG8_MMA(0, 1, At, B1); PG8_BAR;
;             PG8_LDA(At, 0, 1); PG8_STAGE(PG8_SA(0, 0), a2, voffA);
;             PG8_BAR; PG8_WAIT_L(0); PG8_MMA(1, 0, At, B0); PG8_BAR; PG8_SCHED;
;             PG8_STAGE(PG8_SB(0, 1), b2 + hstepB, voffB);
;             PG8_WAIT_V(6); PG8_BAR; PG8_MMA(1, 1, At, B1); PG8_BAR;
;             PG8_LDB(B0, 1, 0); PG8_SCHED; PG8_LDA(At, 1, 0); PG8_STAGE(PG8_SA(0, 1), a2 + hstep, voffA);
;             PG8_WAIT_L(8); PG8_BAR; PG8_WAIT_L(0); PG8_MMA(0, 0, At, B0); PG8_BAR; PG8_SCHED;
;             PG8_LDB(B1, 1, 1); PG8_STAGE(PG8_SB(1, 0), b3, voffB);
;             PG8_BAR; PG8_WAIT_L(0); PG8_MMA(0, 1, At, B1); PG8_BAR;
;             PG8_LDA(At, 1, 1); PG8_STAGE(PG8_SA(1, 0), a3, voffA);
;             PG8_BAR; PG8_WAIT_L(0); PG8_MMA(1, 0, At, B0); PG8_BAR; PG8_SCHED;
;             PG8_STAGE(PG8_SB(1, 1), b3 + hstepB, voffB);
;             PG8_WAIT_V(6); PG8_BAR; PG8_MMA(1, 1, At, B1); PG8_BAR;
;             }
;         }
;         if constexpr (ALIGN_EPI) { if (wr == 0) PG8_BAR; }
	s_add_i32 s14, s58, s24
	v_lshl_add_u64 v[214:215], v[214:215], 0, s[8:9]
	s_mov_b32 m0, s14
	ds_read_b128 v[182:185], v169 offset:49152
	ds_read_b128 v[186:189], v169 offset:50176
	ds_read_b128 v[190:193], v169 offset:51200
	ds_read_b128 v[194:197], v169 offset:52224
	ds_read_b128 v[198:201], v169 offset:53248
	ds_read_b128 v[202:205], v169 offset:54272
	ds_read_b128 v[206:209], v169 offset:55296
	ds_read_b128 v[210:213], v169 offset:56320
	global_load_lds_dwordx4 v[214:215], off
	s_add_i32 m0, s14, 0x2000
	s_add_u32 s14, s18, 0x2b0080
	v_lshl_add_u64 v[214:215], v[216:217], 0, s[8:9]
	s_addc_u32 s15, s19, 0
	s_add_i32 s18, s59, s24
	global_load_lds_dwordx4 v[214:215], off
	v_lshl_add_u64 v[214:215], s[14:15], 0, v[146:147]
	s_mov_b32 m0, s18
	s_nop 0
	global_load_lds_dwordx4 v[214:215], off
	v_lshl_add_u64 v[214:215], s[14:15], 0, v[150:151]
	s_add_i32 m0, s18, 0x2000
	s_nop 0
	global_load_lds_dwordx4 v[214:215], off
	v_lshl_add_u64 v[214:215], v[218:219], 0, s[8:9]
	s_mov_b32 m0, s33
	s_nop 0
	global_load_lds_dwordx4 v[214:215], off
	v_lshl_add_u64 v[214:215], v[220:221], 0, s[8:9]
	s_mov_b32 m0, s34
	s_nop 0
	global_load_lds_dwordx4 v[214:215], off
	s_waitcnt vmcnt(8)
	s_waitcnt lgkmcnt(0)
	s_barrier
	s_setprio 1
	s_waitcnt lgkmcnt(0)
	v_mfma_f32_16x16x32_bf16 v[60:63], v[128:131], v[182:185], v[60:63]
	v_mfma_f32_16x16x32_bf16 v[60:63], v[132:135], v[186:189], v[60:63]
	v_mfma_f32_16x16x32_bf16 v[56:59], v[136:139], v[182:185], v[56:59]
	v_mfma_f32_16x16x32_bf16 v[56:59], v[140:143], v[186:189], v[56:59]
	v_mfma_f32_16x16x32_bf16 v[48:51], v[128:131], v[190:193], v[48:51]
	v_mfma_f32_16x16x32_bf16 v[48:51], v[132:135], v[194:197], v[48:51]
	v_mfma_f32_16x16x32_bf16 v[40:43], v[136:139], v[190:193], v[40:43]
	v_mfma_f32_16x16x32_bf16 v[40:43], v[140:143], v[194:197], v[40:43]
	v_mfma_f32_16x16x32_bf16 v[28:31], v[128:131], v[198:201], v[28:31]
	v_mfma_f32_16x16x32_bf16 v[28:31], v[132:135], v[202:205], v[28:31]
	v_mfma_f32_16x16x32_bf16 v[24:27], v[136:139], v[198:201], v[24:27]
	v_mfma_f32_16x16x32_bf16 v[24:27], v[140:143], v[202:205], v[24:27]
	v_mfma_f32_16x16x32_bf16 v[20:23], v[128:131], v[206:209], v[20:23]
	v_mfma_f32_16x16x32_bf16 v[20:23], v[132:135], v[210:213], v[20:23]
	v_mfma_f32_16x16x32_bf16 v[12:15], v[136:139], v[206:209], v[12:15]
	v_mfma_f32_16x16x32_bf16 v[12:15], v[140:143], v[210:213], v[12:15]
	v_mfma_f32_16x16x32_bf16 v[52:55], v[160:163], v[182:185], v[52:55]
	v_mfma_f32_16x16x32_bf16 v[52:55], v[170:173], v[186:189], v[52:55]
	v_mfma_f32_16x16x32_bf16 v[44:47], v[174:177], v[182:185], v[44:47]
	v_mfma_f32_16x16x32_bf16 v[44:47], v[178:181], v[186:189], v[44:47]
	v_mfma_f32_16x16x32_bf16 v[36:39], v[160:163], v[190:193], v[36:39]
	v_mfma_f32_16x16x32_bf16 v[36:39], v[170:173], v[194:197], v[36:39]
	v_mfma_f32_16x16x32_bf16 v[32:35], v[174:177], v[190:193], v[32:35]
	v_mfma_f32_16x16x32_bf16 v[32:35], v[178:181], v[194:197], v[32:35]
	v_mfma_f32_16x16x32_bf16 v[16:19], v[160:163], v[198:201], v[16:19]
	v_mfma_f32_16x16x32_bf16 v[16:19], v[170:173], v[202:205], v[16:19]
	v_mfma_f32_16x16x32_bf16 v[8:11], v[174:177], v[198:201], v[8:11]
	v_mfma_f32_16x16x32_bf16 v[8:11], v[178:181], v[202:205], v[8:11]
	v_mfma_f32_16x16x32_bf16 v[4:7], v[160:163], v[206:209], v[4:7]
	v_mfma_f32_16x16x32_bf16 v[4:7], v[170:173], v[210:213], v[4:7]
	v_mfma_f32_16x16x32_bf16 v[0:3], v[174:177], v[206:209], v[0:3]
	v_mfma_f32_16x16x32_bf16 v[0:3], v[178:181], v[210:213], v[0:3]
	s_setprio 0
	s_barrier
	s_add_i32 s57, s57, 2
	s_add_u32 s55, s55, 0x100
	s_addc_u32 s56, s56, 0
	s_cmpk_gt_u32 s57, 0xa9
	s_mov_b64 s[14:15], s[16:17]
	s_cbranch_scc0 .LBB0_2165
	s_and_b64 vcc, exec, s[10:11]
	s_cbranch_vccz .LBB0_2168
	s_barrier
